# speedup vs baseline: 1.0189x; 1.0034x over previous
; template <bool BOUND>
; DEV void attn_tile(const char* kb_, const char* vb_, const float* cl, int kt, bool diag, const int (&qrow)[2], int fr, int fq,
;                    const float (&cq2)[2], const bf16x8 (&qf)[2][2], f32x4 (&o)[2][4], float (&m2)[2], float (&l)[2]) {
;     ...
; #pragma unroll
;   for (int s = 0; s < 4; ++s) {
;     const bf16x8 a0 = *(const bf16x8*)(kb_ + (s * 16 + fr) * 144 + fq * 16);
;     const bf16x8 a1 = *(const bf16x8*)(kb_ + (s * 16 + fr) * 144 + 64 + fq * 16);
; #pragma unroll
;     for (int qs = 0; qs < 2; ++qs) {
;       f32x4 z = f32x4{0.f, 0.f, 0.f, 0.f};
;       z = __builtin_amdgcn_mfma_f32_16x16x32_bf16(a0, qf[qs][0], z, 0, 0, 0);
;       st[qs][s] = __builtin_amdgcn_mfma_f32_16x16x32_bf16(a1, qf[qs][1], z, 0, 0, 0);
;     }
;   }
;   bf16x8 vf[4][2];
; #pragma unroll
;   for (int n = 0; n < 4; ++n)
; #pragma unroll
;     for (int g = 0; g < 2; ++g) {
;       const char* va = vb_ + (n * 16 + fr) * 144 + (g * 32 + fq * 4) * 2;
;       union { bf16x8 v; uint2 u[2]; } av;
;       av.u[0] = *(const uint2*)va;
;       av.u[1] = *(const uint2*)(va + 32);
;       vf[n][g] = av.v;
;     }
;   bf16x8 pf[2][2];
; #pragma unroll
;   for (int qs = 0; qs < 2; ++qs) {
;     if constexpr (BOUND) {
;       float ps = 0.f;
; #pragma unroll
;       for (int s = 0; s < 4; ++s) {
;         const float4 ck = *(const float4*)(cl + kt * 64 + s * 16 + fq * 4);
;         const float ckk[4] = {ck.x, ck.y, ck.z, ck.w};
; #pragma unroll
;         for (int j = 0; j < 4; ++j) {
;           float x = st[qs][s][j] * SC2 + (cq2[qs] - ckk[j]);
;           if (diag) {
;             const int key = kt * 64 + s * 16 + fq * 4 + j;
;             if (key > qrow[qs]) x = -1e30f;
;           }
;           const float pv = __builtin_amdgcn_exp2f(x);
;           st[qs][s][j] = pv;
;           ps += pv;
;         }
;       }
;       l[qs] += ps;
;     } else {
;     float tmax = -1e30f;
; #pragma unroll
;     for (int s = 0; s < 4; ++s) {
;       const float4 ck = *(const float4*)(cl + kt * 64 + s * 16 + fq * 4);
;       const float ckk[4] = {ck.x, ck.y, ck.z, ck.w};
; #pragma unroll
;       for (int j = 0; j < 4; ++j) {
;         float x = st[qs][s][j] * SC2 + (cq2[qs] - ckk[j]);
;         if (diag) {
;           const int key = kt * 64 + s * 16 + fq * 4 + j;
;           if (key > qrow[qs]) x = -1e30f;
;         }
;         st[qs][s][j] = x;
.LBB0_819:
	s_bitcmp1_b32 s73, 0
	s_cselect_b32 s23, 0x4800, 0
	s_lshl_b32 s12, s73, 6
	v_cmp_le_i32_e32 vcc, s12, v213
	s_and_saveexec_b64 s[6:7], vcc
	s_cbranch_execz .LBB0_825
	v_add_u32_e32 v72, s23, v211
	v_add_u32_e32 v73, v72, v210
	ds_read_b128 v[132:135], v73
	ds_read_b128 v[128:131], v73 offset:64
	ds_read_b128 v[124:127], v73 offset:2304
	ds_read_b128 v[120:123], v73 offset:2368
	ds_read_b128 v[116:119], v73 offset:4608
	ds_read_b128 v[112:115], v73 offset:4672
	ds_read_b128 v[108:111], v73 offset:6912
	ds_read_b128 v[104:107], v73 offset:6976
	s_waitcnt lgkmcnt(8)
	v_add_u32_e32 v96, v72, v142
	v_add_u32_e32 v72, 0x2000, v96
	ds_read2_b64 v[92:95], v72 offset0:128 offset1:132
	ds_read2_b64 v[88:91], v72 offset0:136 offset1:140
	v_add_u32_e32 v72, 0x2800, v96
	ds_read2_b64 v[84:87], v72 offset0:160 offset1:164
	ds_read2_b64 v[80:83], v72 offset0:168 offset1:172
	v_add_u32_e32 v72, 0x3000, v96
	v_lshl_add_u32 v140, s12, 2, v144
	ds_read2_b64 v[76:79], v72 offset0:192 offset1:196
	ds_read2_b64 v[72:75], v72 offset0:200 offset1:204
	ds_read_b128 v[228:231], v140 offset:36864
	v_add_u32_e32 v96, 0x3800, v96
	ds_read2_b64 v[100:103], v96 offset0:224 offset1:228
	ds_read2_b64 v[96:99], v96 offset0:232 offset1:236
	s_cmp_ge_u32 s73, s70
	s_cselect_b64 vcc, -1, 0
	s_waitcnt lgkmcnt(2)
	v_sub_f32_e32 v137, v157, v228
	v_sub_f32_e32 v139, v157, v229
	v_sub_f32_e32 v138, v157, v230
	v_sub_f32_e32 v136, v157, v231
	v_sub_f32_e32 v228, v177, v228
	v_sub_f32_e32 v227, v177, v229
	v_sub_f32_e32 v226, v177, v230
	v_sub_f32_e32 v225, v177, v231
	s_cbranch_vccz .Lattn_z0
	v_or_b32_e32 v222, s12, v212
	v_cmp_gt_i32_e64 s[12:13], v222, v176
	s_and_b64 s[12:13], vcc, s[12:13]
	v_or_b32_e32 v224, 2, v222
	v_or_b32_e32 v223, 3, v222
	v_or_b32_e32 v183, 16, v222
	v_or_b32_e32 v221, 17, v222
	v_or_b32_e32 v220, 18, v222
	v_or_b32_e32 v219, 19, v222
	v_or_b32_e32 v218, 32, v222
	v_or_b32_e32 v217, 33, v222
	v_or_b32_e32 v216, 34, v222
	v_or_b32_e32 v215, 35, v222
	v_or_b32_e32 v214, 48, v222
	v_or_b32_e32 v186, 49, v222
	v_or_b32_e32 v184, 50, v222
	v_or_b32_e32 v182, 51, v222
	s_branch .Lattn_s0
.Lattn_z0:
	s_mov_b64 s[12:13], 0
.Lattn_s0:
	s_and_saveexec_b64 s[14:15], s[10:11]
	s_xor_b64 s[26:27], exec, s[14:15]
	s_cbranch_execz .LBB0_822
	v_mfma_f32_16x16x32_bf16 v[188:191], v[132:135], v[12:15], 0
	v_cmp_lt_i32_e64 s[14:15], v222, v176
	v_mfma_f32_16x16x32_bf16 v[188:191], v[128:131], v[16:19], v[188:191]
	v_mfma_f32_16x16x32_bf16 v[132:135], v[132:135], v[28:31], 0
	v_mfma_f32_16x16x32_bf16 v[230:233], v[124:127], v[12:15], 0
	s_nop 5
	v_fmac_f32_e32 v137, 0x3e38aa3b, v188
	v_fmac_f32_e32 v139, 0x3e38aa3b, v189
	v_cndmask_b32_e64 v185, v137, v202, s[12:13]
	v_cndmask_b32_e64 v137, v202, v139, s[14:15]
	v_mfma_f32_16x16x32_bf16 v[128:131], v[128:131], v[24:27], v[132:135]
	v_cmp_gt_i32_e64 s[14:15], v224, v176
	v_fmac_f32_e32 v138, 0x3e38aa3b, v190
	s_and_b64 s[14:15], vcc, s[14:15]
	ds_read_b128 v[132:135], v140 offset:36928
	v_cndmask_b32_e64 v229, v138, v202, s[14:15]
	v_fmac_f32_e32 v136, 0x3e38aa3b, v191
	v_cmp_gt_i32_e64 s[14:15], v223, v176
	v_mfma_f32_16x16x32_bf16 v[188:191], v[120:123], v[16:19], v[230:233]
	v_cndmask_b32_e32 v187, v139, v137, vcc
	s_and_b64 s[14:15], vcc, s[14:15]
	v_max3_f32 v137, v185, s89, v187
	v_mfma_f32_16x16x32_bf16 v[124:127], v[124:127], v[28:31], 0
	v_cndmask_b32_e64 v242, v136, v202, s[14:15]
	v_max3_f32 v234, v137, v229, v242
	ds_read_b128 v[136:139], v140 offset:36992
	s_waitcnt lgkmcnt(1)
	v_sub_f32_e32 v235, v157, v132
	v_cmp_gt_i32_e64 s[14:15], v183, v176
	v_fmac_f32_e32 v235, 0x3e38aa3b, v188
	v_mfma_f32_16x16x32_bf16 v[230:233], v[120:123], v[24:27], v[124:127]
	s_and_b64 s[14:15], vcc, s[14:15]
	v_fmac_f32_e32 v228, 0x3e38aa3b, v128
	v_fmac_f32_e32 v227, 0x3e38aa3b, v129
	v_mfma_f32_16x16x32_bf16 v[120:123], v[116:119], v[12:15], 0
	v_cndmask_b32_e64 v124, v235, v202, s[14:15]
	v_sub_f32_e32 v125, v157, v133
	v_cmp_gt_i32_e64 s[14:15], v221, v176
	v_mfma_f32_16x16x32_bf16 v[116:119], v[116:119], v[28:31], 0
	v_fmac_f32_e32 v125, 0x3e38aa3b, v189
	s_and_b64 s[14:15], vcc, s[14:15]
	v_cndmask_b32_e64 v125, v125, v202, s[14:15]
	v_sub_f32_e32 v127, v157, v134
	v_cmp_gt_i32_e64 s[14:15], v220, v176
	v_mfma_f32_16x16x32_bf16 v[120:123], v[112:115], v[16:19], v[120:123]
	v_fmac_f32_e32 v127, 0x3e38aa3b, v190
	s_and_b64 s[14:15], vcc, s[14:15]
	v_max3_f32 v126, v234, v124, v125
	v_cndmask_b32_e64 v243, v127, v202, s[14:15]
	v_mfma_f32_16x16x32_bf16 v[234:237], v[112:115], v[24:27], v[116:119]
	v_cmp_gt_i32_e64 s[14:15], v219, v176
	s_and_b64 s[14:15], vcc, s[14:15]
	v_fmac_f32_e32 v226, 0x3e38aa3b, v130
	v_sub_f32_e32 v116, v157, v135
	v_fmac_f32_e32 v116, 0x3e38aa3b, v191
	v_cndmask_b32_e64 v116, v116, v202, s[14:15]
	s_waitcnt lgkmcnt(0)
	v_sub_f32_e32 v118, v157, v136
	v_cmp_gt_i32_e64 s[14:15], v218, v176
	v_mfma_f32_16x16x32_bf16 v[112:115], v[108:111], v[12:15], 0
	v_fmac_f32_e32 v118, 0x3e38aa3b, v120
	s_and_b64 s[14:15], vcc, s[14:15]
	v_cndmask_b32_e64 v118, v118, v202, s[14:15]
	v_sub_f32_e32 v119, v157, v137
	v_cmp_gt_i32_e64 s[14:15], v217, v176
	v_fmac_f32_e32 v119, 0x3e38aa3b, v121
	s_and_b64 s[14:15], vcc, s[14:15]
	ds_read_b128 v[188:191], v140 offset:37056
	v_cndmask_b32_e64 v120, v119, v202, s[14:15]
	v_sub_f32_e32 v119, v157, v138
	v_cmp_gt_i32_e64 s[14:15], v216, v176
	v_mfma_f32_16x16x32_bf16 v[112:115], v[104:107], v[16:19], v[112:115]
	v_fmac_f32_e32 v119, 0x3e38aa3b, v122
	s_and_b64 s[14:15], vcc, s[14:15]
	v_cndmask_b32_e64 v122, v119, v202, s[14:15]
	v_sub_f32_e32 v119, v157, v139
	v_cmp_gt_i32_e64 s[14:15], v215, v176
	v_fmac_f32_e32 v119, 0x3e38aa3b, v123
	s_and_b64 s[14:15], vcc, s[14:15]
	v_cndmask_b32_e64 v123, v119, v202, s[14:15]
	s_waitcnt lgkmcnt(0)
; template <bool BOUND>
; DEV void attn_tile(const char* kb_, const char* vb_, const float* cl, int kt, bool diag, const int (&qrow)[2], int fr, int fq,
;                    const float (&cq2)[2], const bf16x8 (&qf)[2][2], f32x4 (&o)[2][4], float (&m2)[2], float (&l)[2]) {
;     ...
;     float tmax = -1e30f;
; #pragma unroll
;     for (int s = 0; s < 4; ++s) {
;       const float4 ck = *(const float4*)(cl + kt * 64 + s * 16 + fq * 4);
;       const float ckk[4] = {ck.x, ck.y, ck.z, ck.w};
; #pragma unroll
;       for (int j = 0; j < 4; ++j) {
;         float x = st[qs][s][j] * SC2 + (cq2[qs] - ckk[j]);
;         if (diag) {
;           const int key = kt * 64 + s * 16 + fq * 4 + j;
;           if (key > qrow[qs]) x = -1e30f;
;         }
;         st[qs][s][j] = x;
;         tmax = fmaxf(tmax, x);
;       }
;     }
;     tmax = fmaxf(tmax, __shfl_xor(tmax, 16));
;     tmax = fmaxf(tmax, __shfl_xor(tmax, 32));
;     const float mn = fmaxf(m2[qs], tmax);
;     const float alpha = __builtin_amdgcn_exp2f(m2[qs] - mn);
;     m2[qs] = mn;
;     float ps = 0.f;
; #pragma unroll
;     for (int s = 0; s < 4; ++s)
; #pragma unroll
;       for (int j = 0; j < 4; ++j) {
;         const float pv = __builtin_amdgcn_exp2f(st[qs][s][j] - mn);
;         st[qs][s][j] = pv;
;         ps += pv;
;       }
;     l[qs] = l[qs] * alpha + ps;
; #pragma unroll
;     for (int n = 0; n < 4; ++n) { o[qs][n][0] *= alpha; o[qs][n][1] *= alpha; o[qs][n][2] *= alpha; o[qs][n][3] *= alpha; }
	v_sub_f32_e32 v119, v157, v188
	v_cmp_gt_i32_e64 s[14:15], v214, v176
	v_fmac_f32_e32 v119, 0x3e38aa3b, v112
	s_and_b64 s[14:15], vcc, s[14:15]
	v_cndmask_b32_e64 v112, v119, v202, s[14:15]
	v_sub_f32_e32 v119, v157, v189
	v_cmp_gt_i32_e64 s[14:15], v186, v176
	v_fmac_f32_e32 v119, 0x3e38aa3b, v113
	s_and_b64 s[14:15], vcc, s[14:15]
	v_cndmask_b32_e64 v113, v119, v202, s[14:15]
	v_sub_f32_e32 v119, v157, v190
	v_cmp_gt_i32_e64 s[14:15], v184, v176
	v_max3_f32 v117, v126, v243, v116
	v_fmac_f32_e32 v119, 0x3e38aa3b, v114
	s_and_b64 s[14:15], vcc, s[14:15]
	v_max3_f32 v117, v117, v118, v120
	v_cndmask_b32_e64 v114, v119, v202, s[14:15]
	v_sub_f32_e32 v119, v157, v191
	v_cmp_gt_i32_e64 s[14:15], v182, v176
	v_max3_f32 v117, v117, v122, v123
	v_fmac_f32_e32 v119, 0x3e38aa3b, v115
	s_and_b64 s[14:15], vcc, s[14:15]
	v_max3_f32 v117, v117, v112, v113
	v_cndmask_b32_e64 v126, v119, v202, s[14:15]
	v_max3_f32 v115, v117, v114, v126
	ds_bpermute_b32 v117, v204, v115
	v_mfma_f32_16x16x32_bf16 v[108:111], v[108:111], v[28:31], 0
	v_cmp_gt_i32_e64 s[14:15], v222, v143
	s_and_b64 s[14:15], vcc, s[14:15]
	v_fmac_f32_e32 v225, 0x3e38aa3b, v131
	s_waitcnt lgkmcnt(0)
	v_max_f32_e32 v117, v117, v117
	v_max_f32_e32 v115, v115, v117
	ds_bpermute_b32 v117, v203, v115
	v_mfma_f32_16x16x32_bf16 v[238:241], v[104:107], v[24:27], v[108:111]
	s_waitcnt lgkmcnt(0)
	v_max3_f32 v250, v181, v115, v117
	v_sub_f32_e32 v105, v185, v250
	v_exp_f32_e32 v127, v105
	v_sub_f32_e32 v105, v187, v250
	v_sub_f32_e32 v104, v181, v250
	v_exp_f32_e32 v181, v105
	v_sub_f32_e32 v105, v229, v250
	v_sub_f32_e32 v106, v123, v250
	v_exp_f32_e32 v183, v105
	v_sub_f32_e32 v105, v242, v250
	v_exp_f32_e32 v109, v106
	v_sub_f32_e32 v106, v112, v250
	v_exp_f32_e32 v185, v105
	v_sub_f32_e32 v105, v124, v250
	v_exp_f32_e32 v115, v106
	v_sub_f32_e32 v106, v113, v250
	v_exp_f32_e32 v140, v104
	v_sub_f32_e32 v104, v126, v250
	v_exp_f32_e32 v187, v105
	v_sub_f32_e32 v105, v125, v250
	v_exp_f32_e32 v113, v106
	v_sub_f32_e32 v106, v114, v250
	v_exp_f32_e32 v125, v104
	v_cndmask_b32_e64 v104, v228, v202, s[14:15]
	v_cmp_lt_i32_e64 s[14:15], v222, v143
	v_exp_f32_e32 v123, v106
	v_sub_f32_e32 v114, v177, v133
	v_cndmask_b32_e64 v106, v202, v227, s[14:15]
	v_cmp_gt_i32_e64 s[14:15], v224, v143
	s_and_b64 s[14:15], vcc, s[14:15]
	v_exp_f32_e32 v121, v105
	v_cndmask_b32_e64 v108, v226, v202, s[14:15]
	v_cmp_gt_i32_e64 s[14:15], v223, v143
	s_and_b64 s[14:15], vcc, s[14:15]
	v_sub_f32_e32 v105, v243, v250
	v_cndmask_b32_e64 v110, v225, v202, s[14:15]
	v_cmp_gt_i32_e64 s[14:15], v221, v143
	v_fmac_f32_e32 v114, 0x3e38aa3b, v231
	s_and_b64 s[14:15], vcc, s[14:15]
	v_exp_f32_e32 v107, v105
	v_sub_f32_e32 v105, v116, v250
	v_cndmask_b32_e64 v114, v114, v202, s[14:15]
	v_sub_f32_e32 v116, v177, v134
	v_cmp_gt_i32_e64 s[14:15], v220, v143
	v_fmac_f32_e32 v116, 0x3e38aa3b, v232
	s_and_b64 s[14:15], vcc, s[14:15]
	v_exp_f32_e32 v111, v105
	v_sub_f32_e32 v105, v118, v250
	v_cndmask_b32_e64 v116, v116, v202, s[14:15]
	v_sub_f32_e32 v118, v177, v135
	v_cmp_gt_i32_e64 s[14:15], v219, v143
	v_fmac_f32_e32 v118, 0x3e38aa3b, v233
	s_and_b64 s[14:15], vcc, s[14:15]
	v_exp_f32_e32 v119, v105
	v_sub_f32_e32 v105, v120, v250
	v_cndmask_b32_e64 v118, v118, v202, s[14:15]
	v_sub_f32_e32 v120, v177, v136
	v_cmp_gt_i32_e64 s[14:15], v218, v143
	v_fmac_f32_e32 v120, 0x3e38aa3b, v234
	s_and_b64 s[14:15], vcc, s[14:15]
	v_exp_f32_e32 v117, v105
	v_sub_f32_e32 v105, v122, v250
	v_cndmask_b32_e64 v122, v120, v202, s[14:15]
	v_sub_f32_e32 v120, v177, v137
	v_cmp_gt_i32_e64 s[14:15], v217, v143
	v_fmac_f32_e32 v120, 0x3e38aa3b, v235
	s_and_b64 s[14:15], vcc, s[14:15]
	v_cndmask_b32_e64 v124, v120, v202, s[14:15]
	v_sub_f32_e32 v120, v177, v138
	v_cmp_gt_i32_e64 s[14:15], v216, v143
	v_fmac_f32_e32 v120, 0x3e38aa3b, v236
	s_and_b64 s[14:15], vcc, s[14:15]
	v_cndmask_b32_e64 v130, v120, v202, s[14:15]
	v_sub_f32_e32 v120, v177, v139
	v_cmp_gt_i32_e64 s[14:15], v215, v143
	v_fmac_f32_e32 v120, 0x3e38aa3b, v237
	s_and_b64 s[14:15], vcc, s[14:15]
	v_cndmask_b32_e64 v131, v120, v202, s[14:15]
	v_sub_f32_e32 v120, v177, v188
	v_cmp_gt_i32_e64 s[14:15], v214, v143
	v_fmac_f32_e32 v120, 0x3e38aa3b, v238
	s_and_b64 s[14:15], vcc, s[14:15]
	v_sub_f32_e32 v112, v177, v132
	v_cndmask_b32_e64 v132, v120, v202, s[14:15]
	v_sub_f32_e32 v120, v177, v189
	v_cmp_gt_i32_e64 s[14:15], v186, v143
	v_fmac_f32_e32 v120, 0x3e38aa3b, v239
	s_and_b64 s[14:15], vcc, s[14:15]
	v_cndmask_b32_e64 v133, v120, v202, s[14:15]
	v_sub_f32_e32 v120, v177, v190
	v_cmp_gt_i32_e64 s[14:15], v184, v143
	v_fmac_f32_e32 v120, 0x3e38aa3b, v240
	s_and_b64 s[14:15], vcc, s[14:15]
	v_cndmask_b32_e64 v136, v120, v202, s[14:15]
	v_sub_f32_e32 v120, v177, v191
	v_cmp_gt_i32_e64 s[14:15], v182, v143
	v_cndmask_b32_e32 v106, v227, v106, vcc
	v_fmac_f32_e32 v120, 0x3e38aa3b, v241
	s_and_b64 s[14:15], vcc, s[14:15]
	v_fmac_f32_e32 v112, 0x3e38aa3b, v230
	v_cndmask_b32_e64 v137, v120, v202, s[14:15]
	v_max3_f32 v120, v104, s89, v106
	v_cndmask_b32_e64 v112, v112, v202, s[12:13]
	v_max3_f32 v120, v120, v108, v110
	v_max3_f32 v120, v120, v112, v114
	v_max3_f32 v120, v120, v116, v118
	v_max3_f32 v120, v120, v122, v124
	v_max3_f32 v120, v120, v130, v131
	v_max3_f32 v120, v120, v132, v133
	v_max3_f32 v120, v120, v136, v137
	ds_bpermute_b32 v126, v204, v120
	v_exp_f32_e32 v105, v105
	v_pk_mul_f32 v[70:71], v[70:71], v[140:141] op_sel_hi:[1,0]
	v_pk_mul_f32 v[68:69], v[68:69], v[140:141] op_sel_hi:[1,0]
	v_cvt_pk_bf16_f32 v242, v127, v181
	s_waitcnt lgkmcnt(0)
; template <bool BOUND>
; DEV void attn_tile(const char* kb_, const char* vb_, const float* cl, int kt, bool diag, const int (&qrow)[2], int fr, int fq,
;                    const float (&cq2)[2], const bf16x8 (&qf)[2][2], f32x4 (&o)[2][4], float (&m2)[2], float (&l)[2]) {
;     ...
;     tmax = fmaxf(tmax, __shfl_xor(tmax, 16));
;     tmax = fmaxf(tmax, __shfl_xor(tmax, 32));
;     const float mn = fmaxf(m2[qs], tmax);
;     const float alpha = __builtin_amdgcn_exp2f(m2[qs] - mn);
;     m2[qs] = mn;
;     float ps = 0.f;
; #pragma unroll
;     for (int s = 0; s < 4; ++s)
; #pragma unroll
;       for (int j = 0; j < 4; ++j) {
;         const float pv = __builtin_amdgcn_exp2f(st[qs][s][j] - mn);
;         st[qs][s][j] = pv;
;         ps += pv;
;       }
;     l[qs] = l[qs] * alpha + ps;
; #pragma unroll
;     for (int n = 0; n < 4; ++n) { o[qs][n][0] *= alpha; o[qs][n][1] *= alpha; o[qs][n][2] *= alpha; o[qs][n][3] *= alpha; }
;     }
; #pragma unroll
;     for (int g = 0; g < 2; ++g) {
;       union { bf16x8 v; unsigned u[4]; } pk;
;       pk.u[0] = pack2bf(st[qs][2 * g][0], st[qs][2 * g][1]);
;       pk.u[1] = pack2bf(st[qs][2 * g][2], st[qs][2 * g][3]);
;       pk.u[2] = pack2bf(st[qs][2 * g + 1][0], st[qs][2 * g + 1][1]);
;       pk.u[3] = pack2bf(st[qs][2 * g + 1][2], st[qs][2 * g + 1][3]);
;       pf[qs][g] = pk.v;
;     }
; #pragma unroll
;     for (int n = 0; n < 4; ++n)
; #pragma unroll
;       for (int g = 0; g < 2; ++g) o[qs][n] = __builtin_amdgcn_mfma_f32_16x16x32_bf16(vf[n][g], pf[qs][g], o[qs][n], 0, 0, 0);
	v_max_f32_e32 v126, v126, v126
	v_max_f32_e32 v120, v120, v126
	ds_bpermute_b32 v126, v203, v120
	v_cvt_pk_bf16_f32 v243, v183, v185
	v_cvt_pk_bf16_f32 v244, v187, v121
	v_cvt_pk_bf16_f32 v245, v107, v111
	v_cvt_pk_bf16_f32 v246, v119, v117
	s_waitcnt lgkmcnt(0)
	v_max3_f32 v138, v180, v120, v126
	v_sub_f32_e32 v104, v104, v138
	v_exp_f32_e32 v126, v104
	v_sub_f32_e32 v104, v106, v138
	v_sub_f32_e32 v139, v180, v138
	v_exp_f32_e32 v180, v104
	v_sub_f32_e32 v104, v108, v138
	v_exp_f32_e32 v182, v104
	v_sub_f32_e32 v104, v110, v138
	v_exp_f32_e32 v184, v104
	v_sub_f32_e32 v104, v112, v138
	v_exp_f32_e32 v186, v104
	v_sub_f32_e32 v104, v114, v138
	v_exp_f32_e32 v120, v104
	v_sub_f32_e32 v104, v116, v138
	v_exp_f32_e32 v106, v104
	v_sub_f32_e32 v104, v118, v138
	v_pk_add_f32 v[128:129], v[126:127], 0 op_sel_hi:[1,0]
	v_exp_f32_e32 v110, v104
	v_sub_f32_e32 v104, v122, v138
	v_sub_f32_e32 v122, v136, v138
	v_exp_f32_e32 v136, v139
	v_pk_add_f32 v[128:129], v[180:181], v[128:129]
	v_exp_f32_e32 v118, v104
	v_sub_f32_e32 v104, v124, v138
	v_pk_add_f32 v[128:129], v[182:183], v[128:129]
	v_sub_f32_e32 v112, v132, v138
	v_exp_f32_e32 v116, v104
	v_sub_f32_e32 v104, v130, v138
	v_sub_f32_e32 v108, v131, v138
	v_pk_add_f32 v[128:129], v[184:185], v[128:129]
	v_exp_f32_e32 v114, v112
	v_sub_f32_e32 v112, v133, v138
	v_sub_f32_e32 v124, v137, v138
	v_mov_b32_e32 v137, v140
	v_exp_f32_e32 v104, v104
	v_exp_f32_e32 v108, v108
	v_pk_add_f32 v[134:135], v[186:187], v[128:129]
	v_exp_f32_e32 v112, v112
	v_exp_f32_e32 v122, v122
	v_exp_f32_e32 v124, v124
	v_pk_mul_f32 v[66:67], v[66:67], v[136:137] op_sel_hi:[1,0]
	v_pk_mul_f32 v[64:65], v[64:65], v[136:137] op_sel_hi:[1,0]
	v_cvt_pk_bf16_f32 v126, v126, v180
	v_cvt_pk_bf16_f32 v127, v182, v184
	v_cvt_pk_bf16_f32 v128, v186, v120
	v_cvt_pk_bf16_f32 v129, v106, v110
	v_mfma_f32_16x16x32_bf16 v[68:71], v[92:95], v[242:245], v[68:71]
	v_cvt_pk_bf16_f32 v247, v105, v109
	v_cvt_pk_bf16_f32 v248, v115, v113
	v_cvt_pk_bf16_f32 v249, v123, v125
	v_mfma_f32_16x16x32_bf16 v[64:67], v[92:95], v[126:129], v[64:67]
	v_mul_f32_e64 v42, v42, v140
	v_mul_f32_e64 v43, v43, v140
	v_pk_mul_f32 v[40:41], v[40:41], v[140:141] op_sel_hi:[1,0]
	v_cvt_pk_bf16_f32 v130, v118, v116
	v_cvt_pk_bf16_f32 v131, v104, v108
	v_cvt_pk_bf16_f32 v132, v114, v112
	v_cvt_pk_bf16_f32 v133, v122, v124
	v_pk_mul_f32 v[10:11], v[10:11], v[136:137] op_sel_hi:[1,0]
	v_pk_mul_f32 v[8:9], v[8:9], v[136:137] op_sel_hi:[1,0]
	v_mfma_f32_16x16x32_bf16 v[68:71], v[88:91], v[246:249], v[68:71]
	v_mul_f32_e64 v62, v62, v140
	v_mul_f32_e64 v63, v63, v140
	v_pk_mul_f32 v[60:61], v[60:61], v[140:141] op_sel_hi:[1,0]
	v_pk_mul_f32 v[6:7], v[6:7], v[136:137] op_sel_hi:[1,0]
	v_mfma_f32_16x16x32_bf16 v[40:43], v[84:87], v[242:245], v[40:43]
	v_mul_f32_e64 v4, v4, v136
	v_mul_f32_e64 v5, v5, v136
	v_pk_mul_f32 v[22:23], v[22:23], v[140:141] op_sel_hi:[1,0]
	v_pk_mul_f32 v[20:21], v[20:21], v[140:141] op_sel_hi:[1,0]
	v_mfma_f32_16x16x32_bf16 v[64:67], v[88:91], v[130:133], v[64:67]
	v_add_f32_e64 v88, v120, v134
	v_add_f32_e64 v89, v121, v135
	v_pk_mul_f32 v[2:3], v[2:3], v[136:137] op_sel_hi:[1,0]
	v_pk_mul_f32 v[0:1], v[0:1], v[136:137] op_sel_hi:[1,0]
	v_mfma_f32_16x16x32_bf16 v[8:11], v[84:87], v[126:129], v[8:11]
	v_add_f32_e64 v84, v106, v88
	v_add_f32_e64 v85, v107, v89
	v_mov_b32_e32 v181, v250
	v_pk_add_f32 v[84:85], v[110:111], v[84:85]
	v_mfma_f32_16x16x32_bf16 v[40:43], v[80:83], v[246:249], v[40:43]
	v_add_f32_e64 v84, v118, v84
	v_add_f32_e64 v85, v119, v85
	v_mov_b32_e32 v180, v138
	v_mfma_f32_16x16x32_bf16 v[60:63], v[76:79], v[242:245], v[60:63]
	v_mfma_f32_16x16x32_bf16 v[8:11], v[80:83], v[130:133], v[8:11]
	v_add_f32_e64 v80, v116, v84
	v_add_f32_e64 v81, v117, v85
	v_mfma_f32_16x16x32_bf16 v[4:7], v[76:79], v[126:129], v[4:7]
	v_add_f32_e64 v76, v104, v80
	v_add_f32_e64 v77, v105, v81
	v_pk_add_f32 v[76:77], v[108:109], v[76:77]
	v_mfma_f32_16x16x32_bf16 v[20:23], v[100:103], v[242:245], v[20:23]
	v_add_f32_e64 v76, v114, v76
	v_add_f32_e64 v77, v115, v77
	v_mfma_f32_16x16x32_bf16 v[0:3], v[100:103], v[126:129], v[0:3]
	v_mfma_f32_16x16x32_bf16 v[60:63], v[72:75], v[246:249], v[60:63]
	v_mfma_f32_16x16x32_bf16 v[4:7], v[72:75], v[130:133], v[4:7]
	v_add_f32_e64 v72, v112, v76
	v_add_f32_e64 v73, v113, v77
	v_pk_add_f32 v[72:73], v[122:123], v[72:73]
	v_mfma_f32_16x16x32_bf16 v[20:23], v[96:99], v[246:249], v[20:23]
	v_add_f32_e64 v72, v124, v72
	v_add_f32_e64 v73, v125, v73
	v_pk_fma_f32 v[178:179], v[178:179], v[136:137], v[72:73]
	v_mfma_f32_16x16x32_bf16 v[0:3], v[96:99], v[130:133], v[0:3]

; template <bool BOUND>
; DEV void attn_tile(const char* kb_, const char* vb_, const float* cl, int kt, bool diag, const int (&qrow)[2], int fr, int fq,
;                    const float (&cq2)[2], const bf16x8 (&qf)[2][2], f32x4 (&o)[2][4], float (&m2)[2], float (&l)[2]) {
;     ...
; #pragma unroll
;   for (int s = 0; s < 4; ++s) {
;     const bf16x8 a0 = *(const bf16x8*)(kb_ + (s * 16 + fr) * 144 + fq * 16);
;     const bf16x8 a1 = *(const bf16x8*)(kb_ + (s * 16 + fr) * 144 + 64 + fq * 16);
; #pragma unroll
;     for (int qs = 0; qs < 2; ++qs) {
;       f32x4 z = f32x4{0.f, 0.f, 0.f, 0.f};
;       z = __builtin_amdgcn_mfma_f32_16x16x32_bf16(a0, qf[qs][0], z, 0, 0, 0);
;       st[qs][s] = __builtin_amdgcn_mfma_f32_16x16x32_bf16(a1, qf[qs][1], z, 0, 0, 0);
;     }
;   }
;   bf16x8 vf[4][2];
; #pragma unroll
;   for (int n = 0; n < 4; ++n)
; #pragma unroll
;     for (int g = 0; g < 2; ++g) {
;       const char* va = vb_ + (n * 16 + fr) * 144 + (g * 32 + fq * 4) * 2;
;       union { bf16x8 v; uint2 u[2]; } av;
;       av.u[0] = *(const uint2*)va;
;       av.u[1] = *(const uint2*)(va + 32);
;       vf[n][g] = av.v;
;     }
;   bf16x8 pf[2][2];
; #pragma unroll
;   for (int qs = 0; qs < 2; ++qs) {
;     if constexpr (BOUND) {
;       float ps = 0.f;
; #pragma unroll
;       for (int s = 0; s < 4; ++s) {
;         const float4 ck = *(const float4*)(cl + kt * 64 + s * 16 + fq * 4);
;         const float ckk[4] = {ck.x, ck.y, ck.z, ck.w};
; #pragma unroll
;         for (int j = 0; j < 4; ++j) {
;           float x = st[qs][s][j] * SC2 + (cq2[qs] - ckk[j]);
;           if (diag) {
;             const int key = kt * 64 + s * 16 + fq * 4 + j;
;             if (key > qrow[qs]) x = -1e30f;
;           }
;           const float pv = __builtin_amdgcn_exp2f(x);
;           st[qs][s][j] = pv;
;           ps += pv;
;         }
;       }
;       l[qs] += ps;
;     } else {
;     float tmax = -1e30f;
; #pragma unroll
;     for (int s = 0; s < 4; ++s) {
;       const float4 ck = *(const float4*)(cl + kt * 64 + s * 16 + fq * 4);
;       const float ckk[4] = {ck.x, ck.y, ck.z, ck.w};
; #pragma unroll
;       for (int j = 0; j < 4; ++j) {
;         float x = st[qs][s][j] * SC2 + (cq2[qs] - ckk[j]);
;         if (diag) {
;           const int key = kt * 64 + s * 16 + fq * 4 + j;
;           if (key > qrow[qs]) x = -1e30f;
;         }
;         st[qs][s][j] = x;
.LBB0_842:
	s_bitcmp1_b32 s13, 0
	s_cselect_b32 s14, 0x4800, 0
	v_add_u32_e32 v72, s14, v211
	v_add_u32_e32 v73, v72, v210
	ds_read_b128 v[132:135], v73
	ds_read_b128 v[128:131], v73 offset:64
	ds_read_b128 v[124:127], v73 offset:2304
	ds_read_b128 v[120:123], v73 offset:2368
	ds_read_b128 v[116:119], v73 offset:4608
	ds_read_b128 v[112:115], v73 offset:4672
	ds_read_b128 v[108:111], v73 offset:6912
	ds_read_b128 v[104:107], v73 offset:6976
	s_waitcnt lgkmcnt(8)
	v_add_u32_e32 v96, v72, v142
	v_add_u32_e32 v72, 0x2000, v96
	ds_read2_b64 v[92:95], v72 offset0:128 offset1:132
	ds_read2_b64 v[88:91], v72 offset0:136 offset1:140
	v_add_u32_e32 v72, 0x2800, v96
	ds_read2_b64 v[84:87], v72 offset0:160 offset1:164
	ds_read2_b64 v[80:83], v72 offset0:168 offset1:172
	v_add_u32_e32 v72, 0x3000, v96
	v_lshl_add_u32 v140, s12, 2, v144
	ds_read2_b64 v[76:79], v72 offset0:192 offset1:196
	ds_read2_b64 v[72:75], v72 offset0:200 offset1:204
	ds_read_b128 v[188:191], v140 offset:36864
	v_add_u32_e32 v96, 0x3800, v96
	ds_read2_b64 v[100:103], v96 offset0:224 offset1:228
	ds_read2_b64 v[96:99], v96 offset0:232 offset1:236
	s_cmp_ge_u32 s13, s70
	s_cselect_b64 vcc, -1, 0
	s_waitcnt lgkmcnt(2)
	v_sub_f32_e32 v137, v157, v188
	v_sub_f32_e32 v139, v157, v189
	v_sub_f32_e32 v138, v157, v190
	v_sub_f32_e32 v136, v157, v191
	v_sub_f32_e32 v228, v177, v188
	v_sub_f32_e32 v227, v177, v189
	v_sub_f32_e32 v226, v177, v190
	v_sub_f32_e32 v225, v177, v191
	s_cbranch_vccz .Lattn_z1
	v_or_b32_e32 v222, s12, v212
	v_cmp_gt_i32_e64 s[12:13], v222, v176
	s_and_b64 s[12:13], vcc, s[12:13]
	v_or_b32_e32 v224, 2, v222
	v_or_b32_e32 v223, 3, v222
	v_or_b32_e32 v183, 16, v222
	v_or_b32_e32 v221, 17, v222
	v_or_b32_e32 v220, 18, v222
	v_or_b32_e32 v219, 19, v222
	v_or_b32_e32 v218, 32, v222
	v_or_b32_e32 v217, 33, v222
	v_or_b32_e32 v216, 34, v222
	v_or_b32_e32 v215, 35, v222
	v_or_b32_e32 v214, 48, v222
	v_or_b32_e32 v186, 49, v222
	v_or_b32_e32 v184, 50, v222
	v_or_b32_e32 v182, 51, v222
	s_branch .Lattn_s1

; template <bool BOUND>
; DEV void attn_tile(const char* kb_, const char* vb_, const float* cl, int kt, bool diag, const int (&qrow)[2], int fr, int fq,
;                    const float (&cq2)[2], const bf16x8 (&qf)[2][2], f32x4 (&o)[2][4], float (&m2)[2], float (&l)[2]) {
;     ...
;     const bf16x8 a0 = *(const bf16x8*)(kb_ + (s * 16 + fr) * 144 + fq * 16);
;     const bf16x8 a1 = *(const bf16x8*)(kb_ + (s * 16 + fr) * 144 + 64 + fq * 16);
; #pragma unroll
;     for (int qs = 0; qs < 2; ++qs) {
;       f32x4 z = f32x4{0.f, 0.f, 0.f, 0.f};
;       z = __builtin_amdgcn_mfma_f32_16x16x32_bf16(a0, qf[qs][0], z, 0, 0, 0);
;       st[qs][s] = __builtin_amdgcn_mfma_f32_16x16x32_bf16(a1, qf[qs][1], z, 0, 0, 0);
;     }
;   }
;   bf16x8 vf[4][2];
; #pragma unroll
;   for (int n = 0; n < 4; ++n)
; #pragma unroll
;     for (int g = 0; g < 2; ++g) {
;       const char* va = vb_ + (n * 16 + fr) * 144 + (g * 32 + fq * 4) * 2;
;       union { bf16x8 v; uint2 u[2]; } av;
;       av.u[0] = *(const uint2*)va;
;       av.u[1] = *(const uint2*)(va + 32);
;       vf[n][g] = av.v;
;     }
;   bf16x8 pf[2][2];
; #pragma unroll
;   for (int qs = 0; qs < 2; ++qs) {
;     if constexpr (BOUND) {
;       float ps = 0.f;
; #pragma unroll
;       for (int s = 0; s < 4; ++s) {
;         const float4 ck = *(const float4*)(cl + kt * 64 + s * 16 + fq * 4);
;         const float ckk[4] = {ck.x, ck.y, ck.z, ck.w};
; #pragma unroll
;         for (int j = 0; j < 4; ++j) {
;           float x = st[qs][s][j] * SC2 + (cq2[qs] - ckk[j]);
;           if (diag) {
;             const int key = kt * 64 + s * 16 + fq * 4 + j;
;             if (key > qrow[qs]) x = -1e30f;
;           }
;           const float pv = __builtin_amdgcn_exp2f(x);
;           st[qs][s][j] = pv;
;           ps += pv;
;         }
;       }
;       l[qs] += ps;
;     } else {
;     float tmax = -1e30f;
; #pragma unroll
;     for (int s = 0; s < 4; ++s) {
;       const float4 ck = *(const float4*)(cl + kt * 64 + s * 16 + fq * 4);
;       const float ckk[4] = {ck.x, ck.y, ck.z, ck.w};
; #pragma unroll
;       for (int j = 0; j < 4; ++j) {
;         float x = st[qs][s][j] * SC2 + (cq2[qs] - ckk[j]);
;         if (diag) {
;           const int key = kt * 64 + s * 16 + fq * 4 + j;
;           if (key > qrow[qs]) x = -1e30f;
;         }
;         st[qs][s][j] = x;
;         tmax = fmaxf(tmax, x);
;       }
;     }
.Lattn_s1:
	s_and_saveexec_b64 s[14:15], s[10:11]
	s_xor_b64 s[26:27], exec, s[14:15]
	s_cbranch_execz .LBB0_844
	v_mfma_f32_16x16x32_bf16 v[188:191], v[132:135], v[12:15], 0
	v_cmp_lt_i32_e64 s[14:15], v222, v176
	v_mfma_f32_16x16x32_bf16 v[188:191], v[128:131], v[16:19], v[188:191]
	v_mfma_f32_16x16x32_bf16 v[132:135], v[132:135], v[28:31], 0
	v_mfma_f32_16x16x32_bf16 v[230:233], v[124:127], v[12:15], 0
	s_nop 5
	v_fmac_f32_e32 v137, 0x3e38aa3b, v188
	v_fmac_f32_e32 v139, 0x3e38aa3b, v189
	v_cndmask_b32_e64 v185, v137, v202, s[12:13]
	v_cndmask_b32_e64 v137, v202, v139, s[14:15]
	v_mfma_f32_16x16x32_bf16 v[128:131], v[128:131], v[24:27], v[132:135]
	v_cmp_gt_i32_e64 s[14:15], v224, v176
	v_fmac_f32_e32 v138, 0x3e38aa3b, v190
	s_and_b64 s[14:15], vcc, s[14:15]
	ds_read_b128 v[132:135], v140 offset:36928
	v_cndmask_b32_e64 v229, v138, v202, s[14:15]
	v_fmac_f32_e32 v136, 0x3e38aa3b, v191
	v_cmp_gt_i32_e64 s[14:15], v223, v176
	v_mfma_f32_16x16x32_bf16 v[188:191], v[120:123], v[16:19], v[230:233]
	v_cndmask_b32_e32 v187, v139, v137, vcc
	s_and_b64 s[14:15], vcc, s[14:15]
	v_max3_f32 v137, v185, s89, v187
	v_mfma_f32_16x16x32_bf16 v[124:127], v[124:127], v[28:31], 0
	v_cndmask_b32_e64 v242, v136, v202, s[14:15]
	v_max3_f32 v234, v137, v229, v242
	ds_read_b128 v[136:139], v140 offset:36992
	s_waitcnt lgkmcnt(1)
	v_sub_f32_e32 v235, v157, v132
	v_cmp_gt_i32_e64 s[14:15], v183, v176
	v_fmac_f32_e32 v235, 0x3e38aa3b, v188
	v_mfma_f32_16x16x32_bf16 v[230:233], v[120:123], v[24:27], v[124:127]
	s_and_b64 s[14:15], vcc, s[14:15]
	v_fmac_f32_e32 v228, 0x3e38aa3b, v128
	v_fmac_f32_e32 v227, 0x3e38aa3b, v129
	v_mfma_f32_16x16x32_bf16 v[120:123], v[116:119], v[12:15], 0
	v_cndmask_b32_e64 v124, v235, v202, s[14:15]
	v_sub_f32_e32 v125, v157, v133
	v_cmp_gt_i32_e64 s[14:15], v221, v176
	v_mfma_f32_16x16x32_bf16 v[116:119], v[116:119], v[28:31], 0
	v_fmac_f32_e32 v125, 0x3e38aa3b, v189
	s_and_b64 s[14:15], vcc, s[14:15]
	v_cndmask_b32_e64 v125, v125, v202, s[14:15]
	v_sub_f32_e32 v127, v157, v134
	v_cmp_gt_i32_e64 s[14:15], v220, v176
	v_mfma_f32_16x16x32_bf16 v[120:123], v[112:115], v[16:19], v[120:123]
	v_fmac_f32_e32 v127, 0x3e38aa3b, v190
	s_and_b64 s[14:15], vcc, s[14:15]
	v_max3_f32 v126, v234, v124, v125
	v_cndmask_b32_e64 v243, v127, v202, s[14:15]
	v_mfma_f32_16x16x32_bf16 v[234:237], v[112:115], v[24:27], v[116:119]
	v_cmp_gt_i32_e64 s[14:15], v219, v176
	s_and_b64 s[14:15], vcc, s[14:15]
	v_fmac_f32_e32 v226, 0x3e38aa3b, v130
	v_sub_f32_e32 v116, v157, v135
	v_fmac_f32_e32 v116, 0x3e38aa3b, v191
	v_cndmask_b32_e64 v116, v116, v202, s[14:15]
	s_waitcnt lgkmcnt(0)
	v_sub_f32_e32 v118, v157, v136
	v_cmp_gt_i32_e64 s[14:15], v218, v176
	v_mfma_f32_16x16x32_bf16 v[112:115], v[108:111], v[12:15], 0
	v_fmac_f32_e32 v118, 0x3e38aa3b, v120
	s_and_b64 s[14:15], vcc, s[14:15]
	v_cndmask_b32_e64 v118, v118, v202, s[14:15]
	v_sub_f32_e32 v119, v157, v137
	v_cmp_gt_i32_e64 s[14:15], v217, v176
	v_fmac_f32_e32 v119, 0x3e38aa3b, v121
	s_and_b64 s[14:15], vcc, s[14:15]
	ds_read_b128 v[188:191], v140 offset:37056
	v_cndmask_b32_e64 v120, v119, v202, s[14:15]
	v_sub_f32_e32 v119, v157, v138
	v_cmp_gt_i32_e64 s[14:15], v216, v176
	v_mfma_f32_16x16x32_bf16 v[112:115], v[104:107], v[16:19], v[112:115]
	v_fmac_f32_e32 v119, 0x3e38aa3b, v122
	s_and_b64 s[14:15], vcc, s[14:15]
	v_cndmask_b32_e64 v122, v119, v202, s[14:15]
	v_sub_f32_e32 v119, v157, v139
	v_cmp_gt_i32_e64 s[14:15], v215, v176
	v_fmac_f32_e32 v119, 0x3e38aa3b, v123
	s_and_b64 s[14:15], vcc, s[14:15]
	v_cndmask_b32_e64 v123, v119, v202, s[14:15]
	s_waitcnt lgkmcnt(0)
	v_sub_f32_e32 v119, v157, v188
	v_cmp_gt_i32_e64 s[14:15], v214, v176
	v_fmac_f32_e32 v119, 0x3e38aa3b, v112
	s_and_b64 s[14:15], vcc, s[14:15]
	v_cndmask_b32_e64 v112, v119, v202, s[14:15]
	v_sub_f32_e32 v119, v157, v189
	v_cmp_gt_i32_e64 s[14:15], v186, v176
	v_fmac_f32_e32 v119, 0x3e38aa3b, v113
	s_and_b64 s[14:15], vcc, s[14:15]
	v_cndmask_b32_e64 v113, v119, v202, s[14:15]
	v_sub_f32_e32 v119, v157, v190
	v_cmp_gt_i32_e64 s[14:15], v184, v176
	v_max3_f32 v117, v126, v243, v116
	v_fmac_f32_e32 v119, 0x3e38aa3b, v114
	s_and_b64 s[14:15], vcc, s[14:15]
	v_max3_f32 v117, v117, v118, v120
	v_cndmask_b32_e64 v114, v119, v202, s[14:15]
	v_sub_f32_e32 v119, v157, v191
	v_cmp_gt_i32_e64 s[14:15], v182, v176
	v_max3_f32 v117, v117, v122, v123
	v_fmac_f32_e32 v119, 0x3e38aa3b, v115
	s_and_b64 s[14:15], vcc, s[14:15]
	v_max3_f32 v117, v117, v112, v113
	v_cndmask_b32_e64 v126, v119, v202, s[14:15]
	v_max3_f32 v115, v117, v114, v126
	ds_bpermute_b32 v117, v204, v115
	v_mfma_f32_16x16x32_bf16 v[108:111], v[108:111], v[28:31], 0
	v_cmp_gt_i32_e64 s[14:15], v222, v143
	s_and_b64 s[14:15], vcc, s[14:15]
	v_fmac_f32_e32 v225, 0x3e38aa3b, v131
	s_waitcnt lgkmcnt(0)
	v_max_f32_e32 v117, v117, v117
	v_max_f32_e32 v115, v115, v117
	ds_bpermute_b32 v117, v203, v115
	v_mfma_f32_16x16x32_bf16 v[238:241], v[104:107], v[24:27], v[108:111]
	s_waitcnt lgkmcnt(0)
; template <bool BOUND>
; DEV void attn_tile(const char* kb_, const char* vb_, const float* cl, int kt, bool diag, const int (&qrow)[2], int fr, int fq,
;                    const float (&cq2)[2], const bf16x8 (&qf)[2][2], f32x4 (&o)[2][4], float (&m2)[2], float (&l)[2]) {
;     ...
;     float tmax = -1e30f;
; #pragma unroll
;     for (int s = 0; s < 4; ++s) {
;       const float4 ck = *(const float4*)(cl + kt * 64 + s * 16 + fq * 4);
;       const float ckk[4] = {ck.x, ck.y, ck.z, ck.w};
; #pragma unroll
;       for (int j = 0; j < 4; ++j) {
;         float x = st[qs][s][j] * SC2 + (cq2[qs] - ckk[j]);
;         if (diag) {
;           const int key = kt * 64 + s * 16 + fq * 4 + j;
;           if (key > qrow[qs]) x = -1e30f;
;         }
;         st[qs][s][j] = x;
;         tmax = fmaxf(tmax, x);
;       }
;     }
;     tmax = fmaxf(tmax, __shfl_xor(tmax, 16));
;     tmax = fmaxf(tmax, __shfl_xor(tmax, 32));
;     const float mn = fmaxf(m2[qs], tmax);
;     const float alpha = __builtin_amdgcn_exp2f(m2[qs] - mn);
;     m2[qs] = mn;
;     float ps = 0.f;
; #pragma unroll
;     for (int s = 0; s < 4; ++s)
; #pragma unroll
;       for (int j = 0; j < 4; ++j) {
;         const float pv = __builtin_amdgcn_exp2f(st[qs][s][j] - mn);
;         st[qs][s][j] = pv;
;         ps += pv;
;       }
;     l[qs] = l[qs] * alpha + ps;
; #pragma unroll
;     for (int n = 0; n < 4; ++n) { o[qs][n][0] *= alpha; o[qs][n][1] *= alpha; o[qs][n][2] *= alpha; o[qs][n][3] *= alpha; }
;     }
; #pragma unroll
;     for (int g = 0; g < 2; ++g) {
;       union { bf16x8 v; unsigned u[4]; } pk;
;       pk.u[0] = pack2bf(st[qs][2 * g][0], st[qs][2 * g][1]);
;       pk.u[1] = pack2bf(st[qs][2 * g][2], st[qs][2 * g][3]);
;       pk.u[2] = pack2bf(st[qs][2 * g + 1][0], st[qs][2 * g + 1][1]);
;       pk.u[3] = pack2bf(st[qs][2 * g + 1][2], st[qs][2 * g + 1][3]);
;       pf[qs][g] = pk.v;
;     }
	v_max3_f32 v250, v181, v115, v117
	v_sub_f32_e32 v105, v185, v250
	v_exp_f32_e32 v127, v105
	v_sub_f32_e32 v105, v187, v250
	v_sub_f32_e32 v104, v181, v250
	v_exp_f32_e32 v181, v105
	v_sub_f32_e32 v105, v229, v250
	v_sub_f32_e32 v106, v123, v250
	v_exp_f32_e32 v183, v105
	v_sub_f32_e32 v105, v242, v250
	v_exp_f32_e32 v109, v106
	v_sub_f32_e32 v106, v112, v250
	v_exp_f32_e32 v185, v105
	v_sub_f32_e32 v105, v124, v250
	v_exp_f32_e32 v115, v106
	v_sub_f32_e32 v106, v113, v250
	v_exp_f32_e32 v140, v104
	v_sub_f32_e32 v104, v126, v250
	v_exp_f32_e32 v187, v105
	v_sub_f32_e32 v105, v125, v250
	v_exp_f32_e32 v113, v106
	v_sub_f32_e32 v106, v114, v250
	v_exp_f32_e32 v125, v104
	v_cndmask_b32_e64 v104, v228, v202, s[14:15]
	v_cmp_lt_i32_e64 s[14:15], v222, v143
	v_exp_f32_e32 v123, v106
	v_sub_f32_e32 v114, v177, v133
	v_cndmask_b32_e64 v106, v202, v227, s[14:15]
	v_cmp_gt_i32_e64 s[14:15], v224, v143
	s_and_b64 s[14:15], vcc, s[14:15]
	v_exp_f32_e32 v121, v105
	v_cndmask_b32_e64 v108, v226, v202, s[14:15]
	v_cmp_gt_i32_e64 s[14:15], v223, v143
	s_and_b64 s[14:15], vcc, s[14:15]
	v_sub_f32_e32 v105, v243, v250
	v_cndmask_b32_e64 v110, v225, v202, s[14:15]
	v_cmp_gt_i32_e64 s[14:15], v221, v143
	v_fmac_f32_e32 v114, 0x3e38aa3b, v231
	s_and_b64 s[14:15], vcc, s[14:15]
	v_exp_f32_e32 v107, v105
	v_sub_f32_e32 v105, v116, v250
	v_cndmask_b32_e64 v114, v114, v202, s[14:15]
	v_sub_f32_e32 v116, v177, v134
	v_cmp_gt_i32_e64 s[14:15], v220, v143
	v_fmac_f32_e32 v116, 0x3e38aa3b, v232
	s_and_b64 s[14:15], vcc, s[14:15]
	v_exp_f32_e32 v111, v105
	v_sub_f32_e32 v105, v118, v250
	v_cndmask_b32_e64 v116, v116, v202, s[14:15]
	v_sub_f32_e32 v118, v177, v135
	v_cmp_gt_i32_e64 s[14:15], v219, v143
	v_fmac_f32_e32 v118, 0x3e38aa3b, v233
	s_and_b64 s[14:15], vcc, s[14:15]
	v_exp_f32_e32 v119, v105
	v_sub_f32_e32 v105, v120, v250
	v_cndmask_b32_e64 v118, v118, v202, s[14:15]
	v_sub_f32_e32 v120, v177, v136
	v_cmp_gt_i32_e64 s[14:15], v218, v143
	v_fmac_f32_e32 v120, 0x3e38aa3b, v234
	s_and_b64 s[14:15], vcc, s[14:15]
	v_exp_f32_e32 v117, v105
	v_sub_f32_e32 v105, v122, v250
	v_cndmask_b32_e64 v122, v120, v202, s[14:15]
	v_sub_f32_e32 v120, v177, v137
	v_cmp_gt_i32_e64 s[14:15], v217, v143
	v_fmac_f32_e32 v120, 0x3e38aa3b, v235
	s_and_b64 s[14:15], vcc, s[14:15]
	v_cndmask_b32_e64 v124, v120, v202, s[14:15]
	v_sub_f32_e32 v120, v177, v138
	v_cmp_gt_i32_e64 s[14:15], v216, v143
	v_fmac_f32_e32 v120, 0x3e38aa3b, v236
	s_and_b64 s[14:15], vcc, s[14:15]
	v_cndmask_b32_e64 v130, v120, v202, s[14:15]
	v_sub_f32_e32 v120, v177, v139
	v_cmp_gt_i32_e64 s[14:15], v215, v143
	v_fmac_f32_e32 v120, 0x3e38aa3b, v237
	s_and_b64 s[14:15], vcc, s[14:15]
	v_cndmask_b32_e64 v131, v120, v202, s[14:15]
	v_sub_f32_e32 v120, v177, v188
	v_cmp_gt_i32_e64 s[14:15], v214, v143
	v_fmac_f32_e32 v120, 0x3e38aa3b, v238
	s_and_b64 s[14:15], vcc, s[14:15]
	v_sub_f32_e32 v112, v177, v132
	v_cndmask_b32_e64 v132, v120, v202, s[14:15]
	v_sub_f32_e32 v120, v177, v189
	v_cmp_gt_i32_e64 s[14:15], v186, v143
	v_fmac_f32_e32 v120, 0x3e38aa3b, v239
	s_and_b64 s[14:15], vcc, s[14:15]
	v_cndmask_b32_e64 v133, v120, v202, s[14:15]
	v_sub_f32_e32 v120, v177, v190
	v_cmp_gt_i32_e64 s[14:15], v184, v143
	v_fmac_f32_e32 v120, 0x3e38aa3b, v240
	s_and_b64 s[14:15], vcc, s[14:15]
	v_cndmask_b32_e64 v136, v120, v202, s[14:15]
	v_sub_f32_e32 v120, v177, v191
	v_cmp_gt_i32_e64 s[14:15], v182, v143
	v_cndmask_b32_e32 v106, v227, v106, vcc
	v_fmac_f32_e32 v120, 0x3e38aa3b, v241
	s_and_b64 s[14:15], vcc, s[14:15]
	v_fmac_f32_e32 v112, 0x3e38aa3b, v230
	v_cndmask_b32_e64 v137, v120, v202, s[14:15]
	v_max3_f32 v120, v104, s89, v106
	v_cndmask_b32_e64 v112, v112, v202, s[12:13]
	v_max3_f32 v120, v120, v108, v110
	v_max3_f32 v120, v120, v112, v114
	v_max3_f32 v120, v120, v116, v118
	v_max3_f32 v120, v120, v122, v124
	v_max3_f32 v120, v120, v130, v131
	v_max3_f32 v120, v120, v132, v133
	v_max3_f32 v120, v120, v136, v137
	ds_bpermute_b32 v126, v204, v120
	v_exp_f32_e32 v105, v105
	v_pk_mul_f32 v[70:71], v[70:71], v[140:141] op_sel_hi:[1,0]
	v_pk_mul_f32 v[68:69], v[68:69], v[140:141] op_sel_hi:[1,0]
	v_cvt_pk_bf16_f32 v242, v127, v181
	s_waitcnt lgkmcnt(0)
	v_max_f32_e32 v126, v126, v126
	v_max_f32_e32 v120, v120, v126
	ds_bpermute_b32 v126, v203, v120
	v_cvt_pk_bf16_f32 v243, v183, v185
	v_cvt_pk_bf16_f32 v244, v187, v121
	v_cvt_pk_bf16_f32 v245, v107, v111
	v_cvt_pk_bf16_f32 v246, v119, v117
	s_waitcnt lgkmcnt(0)
; template <bool BOUND>
; DEV void attn_tile(const char* kb_, const char* vb_, const float* cl, int kt, bool diag, const int (&qrow)[2], int fr, int fq,
;                    const float (&cq2)[2], const bf16x8 (&qf)[2][2], f32x4 (&o)[2][4], float (&m2)[2], float (&l)[2]) {
;     ...
;     tmax = fmaxf(tmax, __shfl_xor(tmax, 16));
;     tmax = fmaxf(tmax, __shfl_xor(tmax, 32));
;     const float mn = fmaxf(m2[qs], tmax);
;     const float alpha = __builtin_amdgcn_exp2f(m2[qs] - mn);
;     m2[qs] = mn;
;     float ps = 0.f;
; #pragma unroll
;     for (int s = 0; s < 4; ++s)
; #pragma unroll
;       for (int j = 0; j < 4; ++j) {
;         const float pv = __builtin_amdgcn_exp2f(st[qs][s][j] - mn);
;         st[qs][s][j] = pv;
;         ps += pv;
;       }
;     l[qs] = l[qs] * alpha + ps;
; #pragma unroll
;     for (int n = 0; n < 4; ++n) { o[qs][n][0] *= alpha; o[qs][n][1] *= alpha; o[qs][n][2] *= alpha; o[qs][n][3] *= alpha; }
;     }
; #pragma unroll
;     for (int g = 0; g < 2; ++g) {
;       union { bf16x8 v; unsigned u[4]; } pk;
;       pk.u[0] = pack2bf(st[qs][2 * g][0], st[qs][2 * g][1]);
;       pk.u[1] = pack2bf(st[qs][2 * g][2], st[qs][2 * g][3]);
;       pk.u[2] = pack2bf(st[qs][2 * g + 1][0], st[qs][2 * g + 1][1]);
;       pk.u[3] = pack2bf(st[qs][2 * g + 1][2], st[qs][2 * g + 1][3]);
;       pf[qs][g] = pk.v;
;     }
; #pragma unroll
;     for (int n = 0; n < 4; ++n)
; #pragma unroll
;       for (int g = 0; g < 2; ++g) o[qs][n] = __builtin_amdgcn_mfma_f32_16x16x32_bf16(vf[n][g], pf[qs][g], o[qs][n], 0, 0, 0);
	v_max3_f32 v138, v180, v120, v126
	v_sub_f32_e32 v104, v104, v138
	v_exp_f32_e32 v126, v104
	v_sub_f32_e32 v104, v106, v138
	v_sub_f32_e32 v139, v180, v138
	v_exp_f32_e32 v180, v104
	v_sub_f32_e32 v104, v108, v138
	v_exp_f32_e32 v182, v104
	v_sub_f32_e32 v104, v110, v138
	v_exp_f32_e32 v184, v104
	v_sub_f32_e32 v104, v112, v138
	v_exp_f32_e32 v186, v104
	v_sub_f32_e32 v104, v114, v138
	v_exp_f32_e32 v120, v104
	v_sub_f32_e32 v104, v116, v138
	v_exp_f32_e32 v106, v104
	v_sub_f32_e32 v104, v118, v138
	v_exp_f32_e32 v110, v104
	v_sub_f32_e32 v104, v122, v138
	v_pk_add_f32 v[128:129], v[126:127], 0 op_sel_hi:[1,0]
	v_sub_f32_e32 v122, v136, v138
	v_exp_f32_e32 v136, v139
	v_pk_add_f32 v[128:129], v[180:181], v[128:129]
	v_exp_f32_e32 v118, v104
	v_sub_f32_e32 v104, v124, v138
	v_pk_add_f32 v[128:129], v[182:183], v[128:129]
	v_sub_f32_e32 v112, v132, v138
	v_exp_f32_e32 v116, v104
	v_pk_add_f32 v[128:129], v[184:185], v[128:129]
	v_sub_f32_e32 v104, v130, v138
	v_sub_f32_e32 v108, v131, v138
	v_exp_f32_e32 v114, v112
	v_sub_f32_e32 v112, v133, v138
	v_sub_f32_e32 v124, v137, v138
	v_mov_b32_e32 v137, v140
	v_pk_add_f32 v[134:135], v[186:187], v[128:129]
	v_exp_f32_e32 v104, v104
	v_exp_f32_e32 v108, v108
	v_exp_f32_e32 v112, v112
	v_exp_f32_e32 v122, v122
	v_exp_f32_e32 v124, v124
	v_pk_mul_f32 v[66:67], v[66:67], v[136:137] op_sel_hi:[1,0]
	v_pk_mul_f32 v[64:65], v[64:65], v[136:137] op_sel_hi:[1,0]
	v_cvt_pk_bf16_f32 v126, v126, v180
	v_cvt_pk_bf16_f32 v127, v182, v184
	v_cvt_pk_bf16_f32 v128, v186, v120
	v_cvt_pk_bf16_f32 v129, v106, v110
	v_mfma_f32_16x16x32_bf16 v[68:71], v[92:95], v[242:245], v[68:71]
	v_cvt_pk_bf16_f32 v247, v105, v109
	v_cvt_pk_bf16_f32 v248, v115, v113
	v_cvt_pk_bf16_f32 v249, v123, v125
	v_mfma_f32_16x16x32_bf16 v[64:67], v[92:95], v[126:129], v[64:67]
	v_mul_f32_e64 v42, v42, v140
	v_mul_f32_e64 v43, v43, v140
	v_pk_mul_f32 v[40:41], v[40:41], v[140:141] op_sel_hi:[1,0]
	v_cvt_pk_bf16_f32 v130, v118, v116
	v_cvt_pk_bf16_f32 v131, v104, v108
	v_cvt_pk_bf16_f32 v132, v114, v112
	v_cvt_pk_bf16_f32 v133, v122, v124
	v_pk_mul_f32 v[10:11], v[10:11], v[136:137] op_sel_hi:[1,0]
	v_pk_mul_f32 v[8:9], v[8:9], v[136:137] op_sel_hi:[1,0]
	v_mfma_f32_16x16x32_bf16 v[68:71], v[88:91], v[246:249], v[68:71]
	v_mul_f32_e64 v62, v62, v140
	v_mul_f32_e64 v63, v63, v140
	v_pk_mul_f32 v[60:61], v[60:61], v[140:141] op_sel_hi:[1,0]
	v_pk_mul_f32 v[6:7], v[6:7], v[136:137] op_sel_hi:[1,0]
	v_mfma_f32_16x16x32_bf16 v[40:43], v[84:87], v[242:245], v[40:43]
	v_mul_f32_e64 v4, v4, v136
	v_mul_f32_e64 v5, v5, v136
	v_pk_mul_f32 v[22:23], v[22:23], v[140:141] op_sel_hi:[1,0]
	v_pk_mul_f32 v[20:21], v[20:21], v[140:141] op_sel_hi:[1,0]
	v_mfma_f32_16x16x32_bf16 v[64:67], v[88:91], v[130:133], v[64:67]
	v_add_f32_e64 v88, v120, v134
	v_add_f32_e64 v89, v121, v135
	v_pk_mul_f32 v[2:3], v[2:3], v[136:137] op_sel_hi:[1,0]
	v_pk_mul_f32 v[0:1], v[0:1], v[136:137] op_sel_hi:[1,0]
	v_mfma_f32_16x16x32_bf16 v[8:11], v[84:87], v[126:129], v[8:11]
	v_add_f32_e64 v84, v106, v88
	v_add_f32_e64 v85, v107, v89
	v_mov_b32_e32 v181, v250
	v_pk_add_f32 v[84:85], v[110:111], v[84:85]
	v_mfma_f32_16x16x32_bf16 v[40:43], v[80:83], v[246:249], v[40:43]
	v_add_f32_e64 v84, v118, v84
	v_add_f32_e64 v85, v119, v85
	v_mov_b32_e32 v180, v138
	v_mfma_f32_16x16x32_bf16 v[60:63], v[76:79], v[242:245], v[60:63]
	v_mfma_f32_16x16x32_bf16 v[8:11], v[80:83], v[130:133], v[8:11]
	v_add_f32_e64 v80, v116, v84
	v_add_f32_e64 v81, v117, v85
	v_mfma_f32_16x16x32_bf16 v[4:7], v[76:79], v[126:129], v[4:7]
	v_add_f32_e64 v76, v104, v80
	v_add_f32_e64 v77, v105, v81
	v_pk_add_f32 v[76:77], v[108:109], v[76:77]
	v_mfma_f32_16x16x32_bf16 v[20:23], v[100:103], v[242:245], v[20:23]
	v_add_f32_e64 v76, v114, v76
	v_add_f32_e64 v77, v115, v77
	v_mfma_f32_16x16x32_bf16 v[0:3], v[100:103], v[126:129], v[0:3]
	v_mfma_f32_16x16x32_bf16 v[60:63], v[72:75], v[246:249], v[60:63]
	v_mfma_f32_16x16x32_bf16 v[4:7], v[72:75], v[130:133], v[4:7]
	v_add_f32_e64 v72, v112, v76
	v_add_f32_e64 v73, v113, v77
	v_pk_add_f32 v[72:73], v[122:123], v[72:73]
	v_mfma_f32_16x16x32_bf16 v[20:23], v[96:99], v[246:249], v[20:23]
	v_add_f32_e64 v72, v124, v72
	v_add_f32_e64 v73, v125, v73
	v_pk_fma_f32 v[178:179], v[178:179], v[136:137], v[72:73]
	v_mfma_f32_16x16x32_bf16 v[0:3], v[96:99], v[130:133], v[0:3]

; template <bool BOUND>
; DEV void attn_tile(const char* kb_, const char* vb_, const float* cl, int kt, bool diag, const int (&qrow)[2], int fr, int fq,
;                    const float (&cq2)[2], const bf16x8 (&qf)[2][2], f32x4 (&o)[2][4], float (&m2)[2], float (&l)[2]) {
;     ...
; #pragma unroll
;   for (int s = 0; s < 4; ++s) {
;     const bf16x8 a0 = *(const bf16x8*)(kb_ + (s * 16 + fr) * 144 + fq * 16);
;     const bf16x8 a1 = *(const bf16x8*)(kb_ + (s * 16 + fr) * 144 + 64 + fq * 16);
; #pragma unroll
;     for (int qs = 0; qs < 2; ++qs) {
;       f32x4 z = f32x4{0.f, 0.f, 0.f, 0.f};
;       z = __builtin_amdgcn_mfma_f32_16x16x32_bf16(a0, qf[qs][0], z, 0, 0, 0);
;       st[qs][s] = __builtin_amdgcn_mfma_f32_16x16x32_bf16(a1, qf[qs][1], z, 0, 0, 0);
;     }
;   }
;   bf16x8 vf[4][2];
; #pragma unroll
;   for (int n = 0; n < 4; ++n)
; #pragma unroll
;     for (int g = 0; g < 2; ++g) {
;       const char* va = vb_ + (n * 16 + fr) * 144 + (g * 32 + fq * 4) * 2;
;       union { bf16x8 v; uint2 u[2]; } av;
;       av.u[0] = *(const uint2*)va;
;       av.u[1] = *(const uint2*)(va + 32);
;       vf[n][g] = av.v;
;     }
;   bf16x8 pf[2][2];
; #pragma unroll
;   for (int qs = 0; qs < 2; ++qs) {
;     if constexpr (BOUND) {
;       float ps = 0.f;
; #pragma unroll
;       for (int s = 0; s < 4; ++s) {
;         const float4 ck = *(const float4*)(cl + kt * 64 + s * 16 + fq * 4);
;         const float ckk[4] = {ck.x, ck.y, ck.z, ck.w};
; #pragma unroll
;         for (int j = 0; j < 4; ++j) {
;           float x = st[qs][s][j] * SC2 + (cq2[qs] - ckk[j]);
;           if (diag) {
;             const int key = kt * 64 + s * 16 + fq * 4 + j;
;             if (key > qrow[qs]) x = -1e30f;
;           }
;           const float pv = __builtin_amdgcn_exp2f(x);
;           st[qs][s][j] = pv;
;           ps += pv;
;         }
;       }
;       l[qs] += ps;
;     } else {
;     float tmax = -1e30f;
; #pragma unroll
;     for (int s = 0; s < 4; ++s) {
;       const float4 ck = *(const float4*)(cl + kt * 64 + s * 16 + fq * 4);
;       const float ckk[4] = {ck.x, ck.y, ck.z, ck.w};
; #pragma unroll
;       for (int j = 0; j < 4; ++j) {
;         float x = st[qs][s][j] * SC2 + (cq2[qs] - ckk[j]);
;         if (diag) {
;           const int key = kt * 64 + s * 16 + fq * 4 + j;
;           if (key > qrow[qs]) x = -1e30f;
;         }
;         st[qs][s][j] = x;
.LBB0_848:
	v_add_u32_e32 v72, s23, v211
	v_add_u32_e32 v73, v72, v210
	ds_read_b128 v[132:135], v73
	ds_read_b128 v[128:131], v73 offset:64
	ds_read_b128 v[124:127], v73 offset:2304
	ds_read_b128 v[120:123], v73 offset:2368
	ds_read_b128 v[116:119], v73 offset:4608
	ds_read_b128 v[112:115], v73 offset:4672
	ds_read_b128 v[108:111], v73 offset:6912
	ds_read_b128 v[104:107], v73 offset:6976
	s_waitcnt lgkmcnt(8)
	v_add_u32_e32 v96, v72, v142
	v_add_u32_e32 v72, 0x2000, v96
	ds_read2_b64 v[92:95], v72 offset0:128 offset1:132
	ds_read2_b64 v[88:91], v72 offset0:136 offset1:140
	v_add_u32_e32 v72, 0x2800, v96
	ds_read2_b64 v[84:87], v72 offset0:160 offset1:164
	ds_read2_b64 v[80:83], v72 offset0:168 offset1:172
	v_add_u32_e32 v72, 0x3000, v96
	v_lshl_add_u32 v140, s12, 2, v144
	ds_read2_b64 v[76:79], v72 offset0:192 offset1:196
	ds_read2_b64 v[72:75], v72 offset0:200 offset1:204
	ds_read_b128 v[188:191], v140 offset:36864
	v_add_u32_e32 v96, 0x3800, v96
	ds_read2_b64 v[100:103], v96 offset0:224 offset1:228
	ds_read2_b64 v[96:99], v96 offset0:232 offset1:236
	s_cmp_ge_u32 s13, s70
	s_cselect_b64 vcc, -1, 0
	s_waitcnt lgkmcnt(2)
	v_sub_f32_e32 v137, v157, v188
	v_sub_f32_e32 v139, v157, v189
	v_sub_f32_e32 v138, v157, v190
	v_sub_f32_e32 v136, v157, v191
	v_sub_f32_e32 v228, v177, v188
	v_sub_f32_e32 v227, v177, v189
	v_sub_f32_e32 v226, v177, v190
	v_sub_f32_e32 v225, v177, v191
	s_cbranch_vccz .Lattn_z2
	v_or_b32_e32 v222, s12, v212
	v_cmp_gt_i32_e64 s[12:13], v222, v176
	s_and_b64 s[12:13], vcc, s[12:13]
	v_or_b32_e32 v224, 2, v222
	v_or_b32_e32 v223, 3, v222
	v_or_b32_e32 v183, 16, v222
	v_or_b32_e32 v221, 17, v222
	v_or_b32_e32 v220, 18, v222
	v_or_b32_e32 v219, 19, v222
	v_or_b32_e32 v218, 32, v222
	v_or_b32_e32 v217, 33, v222
	v_or_b32_e32 v216, 34, v222
	v_or_b32_e32 v215, 35, v222
	v_or_b32_e32 v214, 48, v222
	v_or_b32_e32 v186, 49, v222
	v_or_b32_e32 v184, 50, v222
	v_or_b32_e32 v182, 51, v222
	s_branch .Lattn_s2

; template <bool BOUND>
; DEV void attn_tile(const char* kb_, const char* vb_, const float* cl, int kt, bool diag, const int (&qrow)[2], int fr, int fq,
;                    const float (&cq2)[2], const bf16x8 (&qf)[2][2], f32x4 (&o)[2][4], float (&m2)[2], float (&l)[2]) {
;     ...
; #pragma unroll
;   for (int s = 0; s < 4; ++s) {
;     const bf16x8 a0 = *(const bf16x8*)(kb_ + (s * 16 + fr) * 144 + fq * 16);
;     const bf16x8 a1 = *(const bf16x8*)(kb_ + (s * 16 + fr) * 144 + 64 + fq * 16);
; #pragma unroll
;     for (int qs = 0; qs < 2; ++qs) {
;       f32x4 z = f32x4{0.f, 0.f, 0.f, 0.f};
;       z = __builtin_amdgcn_mfma_f32_16x16x32_bf16(a0, qf[qs][0], z, 0, 0, 0);
;       st[qs][s] = __builtin_amdgcn_mfma_f32_16x16x32_bf16(a1, qf[qs][1], z, 0, 0, 0);
;     }
;   }
;   bf16x8 vf[4][2];
; #pragma unroll
;   for (int n = 0; n < 4; ++n)
; #pragma unroll
;     for (int g = 0; g < 2; ++g) {
;       const char* va = vb_ + (n * 16 + fr) * 144 + (g * 32 + fq * 4) * 2;
;       union { bf16x8 v; uint2 u[2]; } av;
;       av.u[0] = *(const uint2*)va;
;       av.u[1] = *(const uint2*)(va + 32);
;       vf[n][g] = av.v;
;     }
;   bf16x8 pf[2][2];
; #pragma unroll
;   for (int qs = 0; qs < 2; ++qs) {
;     if constexpr (BOUND) {
;       float ps = 0.f;
; #pragma unroll
;       for (int s = 0; s < 4; ++s) {
;         const float4 ck = *(const float4*)(cl + kt * 64 + s * 16 + fq * 4);
;         const float ckk[4] = {ck.x, ck.y, ck.z, ck.w};
; #pragma unroll
;         for (int j = 0; j < 4; ++j) {
;           float x = st[qs][s][j] * SC2 + (cq2[qs] - ckk[j]);
;           if (diag) {
;             const int key = kt * 64 + s * 16 + fq * 4 + j;
;             if (key > qrow[qs]) x = -1e30f;
;           }
;           const float pv = __builtin_amdgcn_exp2f(x);
;           st[qs][s][j] = pv;
;           ps += pv;
;         }
;       }
;       l[qs] += ps;
;     } else {
;     float tmax = -1e30f;
; #pragma unroll
;     for (int s = 0; s < 4; ++s) {
;       const float4 ck = *(const float4*)(cl + kt * 64 + s * 16 + fq * 4);
;       const float ckk[4] = {ck.x, ck.y, ck.z, ck.w};
; #pragma unroll
;       for (int j = 0; j < 4; ++j) {
;         float x = st[qs][s][j] * SC2 + (cq2[qs] - ckk[j]);
;         if (diag) {
;           const int key = kt * 64 + s * 16 + fq * 4 + j;
;           if (key > qrow[qs]) x = -1e30f;
;         }
;         st[qs][s][j] = x;
.Lattn_s2:
	s_and_saveexec_b64 s[14:15], s[10:11]
	s_xor_b64 s[26:27], exec, s[14:15]
	s_cbranch_execz .LBB0_850
	v_mfma_f32_16x16x32_bf16 v[188:191], v[132:135], v[12:15], 0
	v_cmp_lt_i32_e64 s[14:15], v222, v176
	v_mfma_f32_16x16x32_bf16 v[188:191], v[128:131], v[16:19], v[188:191]
	v_mfma_f32_16x16x32_bf16 v[132:135], v[132:135], v[28:31], 0
	v_mfma_f32_16x16x32_bf16 v[230:233], v[124:127], v[12:15], 0
	s_nop 5
	v_fmac_f32_e32 v137, 0x3e38aa3b, v188
	v_fmac_f32_e32 v139, 0x3e38aa3b, v189
	v_cndmask_b32_e64 v185, v137, v202, s[12:13]
	v_cndmask_b32_e64 v137, v202, v139, s[14:15]
	v_mfma_f32_16x16x32_bf16 v[128:131], v[128:131], v[24:27], v[132:135]
	v_cmp_gt_i32_e64 s[14:15], v224, v176
	v_fmac_f32_e32 v138, 0x3e38aa3b, v190
	s_and_b64 s[14:15], vcc, s[14:15]
	ds_read_b128 v[132:135], v140 offset:36928
	v_cndmask_b32_e64 v229, v138, v202, s[14:15]
	v_fmac_f32_e32 v136, 0x3e38aa3b, v191
	v_cmp_gt_i32_e64 s[14:15], v223, v176
	v_mfma_f32_16x16x32_bf16 v[188:191], v[120:123], v[16:19], v[230:233]
	v_cndmask_b32_e32 v187, v139, v137, vcc
	s_and_b64 s[14:15], vcc, s[14:15]
	v_max3_f32 v137, v185, s89, v187
	v_mfma_f32_16x16x32_bf16 v[124:127], v[124:127], v[28:31], 0
	v_cndmask_b32_e64 v242, v136, v202, s[14:15]
	v_max3_f32 v234, v137, v229, v242
	ds_read_b128 v[136:139], v140 offset:36992
	s_waitcnt lgkmcnt(1)
	v_sub_f32_e32 v235, v157, v132
	v_cmp_gt_i32_e64 s[14:15], v183, v176
	v_fmac_f32_e32 v235, 0x3e38aa3b, v188
	v_mfma_f32_16x16x32_bf16 v[230:233], v[120:123], v[24:27], v[124:127]
	s_and_b64 s[14:15], vcc, s[14:15]
	v_fmac_f32_e32 v228, 0x3e38aa3b, v128
	v_fmac_f32_e32 v227, 0x3e38aa3b, v129
	v_mfma_f32_16x16x32_bf16 v[120:123], v[116:119], v[12:15], 0
	v_cndmask_b32_e64 v124, v235, v202, s[14:15]
	v_sub_f32_e32 v125, v157, v133
	v_cmp_gt_i32_e64 s[14:15], v221, v176
	v_mfma_f32_16x16x32_bf16 v[116:119], v[116:119], v[28:31], 0
	v_fmac_f32_e32 v125, 0x3e38aa3b, v189
	s_and_b64 s[14:15], vcc, s[14:15]
	v_cndmask_b32_e64 v125, v125, v202, s[14:15]
	v_sub_f32_e32 v127, v157, v134
	v_cmp_gt_i32_e64 s[14:15], v220, v176
	v_mfma_f32_16x16x32_bf16 v[120:123], v[112:115], v[16:19], v[120:123]
	v_fmac_f32_e32 v127, 0x3e38aa3b, v190
	s_and_b64 s[14:15], vcc, s[14:15]
	v_max3_f32 v126, v234, v124, v125
	v_cndmask_b32_e64 v243, v127, v202, s[14:15]
	v_mfma_f32_16x16x32_bf16 v[234:237], v[112:115], v[24:27], v[116:119]
	v_cmp_gt_i32_e64 s[14:15], v219, v176
	s_and_b64 s[14:15], vcc, s[14:15]
	v_fmac_f32_e32 v226, 0x3e38aa3b, v130
	v_sub_f32_e32 v116, v157, v135
	v_fmac_f32_e32 v116, 0x3e38aa3b, v191
	v_cndmask_b32_e64 v116, v116, v202, s[14:15]
	s_waitcnt lgkmcnt(0)
	v_sub_f32_e32 v118, v157, v136
	v_cmp_gt_i32_e64 s[14:15], v218, v176
	v_mfma_f32_16x16x32_bf16 v[112:115], v[108:111], v[12:15], 0
	v_fmac_f32_e32 v118, 0x3e38aa3b, v120
	s_and_b64 s[14:15], vcc, s[14:15]
	v_cndmask_b32_e64 v118, v118, v202, s[14:15]
	v_sub_f32_e32 v119, v157, v137
	v_cmp_gt_i32_e64 s[14:15], v217, v176
	v_fmac_f32_e32 v119, 0x3e38aa3b, v121
	s_and_b64 s[14:15], vcc, s[14:15]
	ds_read_b128 v[188:191], v140 offset:37056
	v_cndmask_b32_e64 v120, v119, v202, s[14:15]
	v_sub_f32_e32 v119, v157, v138
	v_cmp_gt_i32_e64 s[14:15], v216, v176
	v_mfma_f32_16x16x32_bf16 v[112:115], v[104:107], v[16:19], v[112:115]
	v_fmac_f32_e32 v119, 0x3e38aa3b, v122
	s_and_b64 s[14:15], vcc, s[14:15]
	v_cndmask_b32_e64 v122, v119, v202, s[14:15]
	v_sub_f32_e32 v119, v157, v139
	v_cmp_gt_i32_e64 s[14:15], v215, v176
	v_fmac_f32_e32 v119, 0x3e38aa3b, v123
	s_and_b64 s[14:15], vcc, s[14:15]
	v_cndmask_b32_e64 v123, v119, v202, s[14:15]
	s_waitcnt lgkmcnt(0)
	v_sub_f32_e32 v119, v157, v188
	v_cmp_gt_i32_e64 s[14:15], v214, v176
	v_fmac_f32_e32 v119, 0x3e38aa3b, v112
	s_and_b64 s[14:15], vcc, s[14:15]
	v_cndmask_b32_e64 v112, v119, v202, s[14:15]
	v_sub_f32_e32 v119, v157, v189
	v_cmp_gt_i32_e64 s[14:15], v186, v176
	v_fmac_f32_e32 v119, 0x3e38aa3b, v113
	s_and_b64 s[14:15], vcc, s[14:15]
	v_cndmask_b32_e64 v113, v119, v202, s[14:15]
	v_sub_f32_e32 v119, v157, v190
	v_cmp_gt_i32_e64 s[14:15], v184, v176
	v_max3_f32 v117, v126, v243, v116
	v_fmac_f32_e32 v119, 0x3e38aa3b, v114
	s_and_b64 s[14:15], vcc, s[14:15]
	v_max3_f32 v117, v117, v118, v120
	v_cndmask_b32_e64 v114, v119, v202, s[14:15]
	v_sub_f32_e32 v119, v157, v191
	v_cmp_gt_i32_e64 s[14:15], v182, v176
	v_max3_f32 v117, v117, v122, v123
	v_fmac_f32_e32 v119, 0x3e38aa3b, v115
	s_and_b64 s[14:15], vcc, s[14:15]
	v_max3_f32 v117, v117, v112, v113
	v_cndmask_b32_e64 v126, v119, v202, s[14:15]
	v_max3_f32 v115, v117, v114, v126
	ds_bpermute_b32 v117, v204, v115
	v_mfma_f32_16x16x32_bf16 v[108:111], v[108:111], v[28:31], 0
	v_cmp_gt_i32_e64 s[14:15], v222, v143
	s_and_b64 s[14:15], vcc, s[14:15]
	v_fmac_f32_e32 v225, 0x3e38aa3b, v131
	s_waitcnt lgkmcnt(0)
	v_max_f32_e32 v117, v117, v117
	v_max_f32_e32 v115, v115, v117
	ds_bpermute_b32 v117, v203, v115
	v_mfma_f32_16x16x32_bf16 v[238:241], v[104:107], v[24:27], v[108:111]
	s_waitcnt lgkmcnt(0)
; template <bool BOUND>
; DEV void attn_tile(const char* kb_, const char* vb_, const float* cl, int kt, bool diag, const int (&qrow)[2], int fr, int fq,
;                    const float (&cq2)[2], const bf16x8 (&qf)[2][2], f32x4 (&o)[2][4], float (&m2)[2], float (&l)[2]) {
;     ...
;     float tmax = -1e30f;
; #pragma unroll
;     for (int s = 0; s < 4; ++s) {
;       const float4 ck = *(const float4*)(cl + kt * 64 + s * 16 + fq * 4);
;       const float ckk[4] = {ck.x, ck.y, ck.z, ck.w};
; #pragma unroll
;       for (int j = 0; j < 4; ++j) {
;         float x = st[qs][s][j] * SC2 + (cq2[qs] - ckk[j]);
;         if (diag) {
;           const int key = kt * 64 + s * 16 + fq * 4 + j;
;           if (key > qrow[qs]) x = -1e30f;
;         }
;         st[qs][s][j] = x;
;         tmax = fmaxf(tmax, x);
;       }
;     }
;     tmax = fmaxf(tmax, __shfl_xor(tmax, 16));
;     tmax = fmaxf(tmax, __shfl_xor(tmax, 32));
;     const float mn = fmaxf(m2[qs], tmax);
;     const float alpha = __builtin_amdgcn_exp2f(m2[qs] - mn);
;     m2[qs] = mn;
;     float ps = 0.f;
; #pragma unroll
;     for (int s = 0; s < 4; ++s)
; #pragma unroll
;       for (int j = 0; j < 4; ++j) {
;         const float pv = __builtin_amdgcn_exp2f(st[qs][s][j] - mn);
;         st[qs][s][j] = pv;
;         ps += pv;
;       }
;     l[qs] = l[qs] * alpha + ps;
; #pragma unroll
;     for (int n = 0; n < 4; ++n) { o[qs][n][0] *= alpha; o[qs][n][1] *= alpha; o[qs][n][2] *= alpha; o[qs][n][3] *= alpha; }
	v_max3_f32 v250, v181, v115, v117
	v_sub_f32_e32 v105, v185, v250
	v_exp_f32_e32 v127, v105
	v_sub_f32_e32 v105, v187, v250
	v_sub_f32_e32 v104, v181, v250
	v_exp_f32_e32 v181, v105
	v_sub_f32_e32 v105, v229, v250
	v_sub_f32_e32 v106, v123, v250
	v_exp_f32_e32 v183, v105
	v_sub_f32_e32 v105, v242, v250
	v_exp_f32_e32 v109, v106
	v_sub_f32_e32 v106, v112, v250
	v_exp_f32_e32 v185, v105
	v_sub_f32_e32 v105, v124, v250
	v_exp_f32_e32 v115, v106
	v_sub_f32_e32 v106, v113, v250
	v_exp_f32_e32 v140, v104
	v_sub_f32_e32 v104, v126, v250
	v_exp_f32_e32 v187, v105
	v_sub_f32_e32 v105, v125, v250
	v_exp_f32_e32 v113, v106
	v_sub_f32_e32 v106, v114, v250
	v_exp_f32_e32 v125, v104
	v_cndmask_b32_e64 v104, v228, v202, s[14:15]
	v_cmp_lt_i32_e64 s[14:15], v222, v143
	v_exp_f32_e32 v123, v106
	v_sub_f32_e32 v114, v177, v133
	v_cndmask_b32_e64 v106, v202, v227, s[14:15]
	v_cmp_gt_i32_e64 s[14:15], v224, v143
	s_and_b64 s[14:15], vcc, s[14:15]
	v_exp_f32_e32 v121, v105
	v_cndmask_b32_e64 v108, v226, v202, s[14:15]
	v_cmp_gt_i32_e64 s[14:15], v223, v143
	s_and_b64 s[14:15], vcc, s[14:15]
	v_sub_f32_e32 v105, v243, v250
	v_cndmask_b32_e64 v110, v225, v202, s[14:15]
	v_cmp_gt_i32_e64 s[14:15], v221, v143
	v_fmac_f32_e32 v114, 0x3e38aa3b, v231
	s_and_b64 s[14:15], vcc, s[14:15]
	v_exp_f32_e32 v107, v105
	v_sub_f32_e32 v105, v116, v250
	v_cndmask_b32_e64 v114, v114, v202, s[14:15]
	v_sub_f32_e32 v116, v177, v134
	v_cmp_gt_i32_e64 s[14:15], v220, v143
	v_fmac_f32_e32 v116, 0x3e38aa3b, v232
	s_and_b64 s[14:15], vcc, s[14:15]
	v_exp_f32_e32 v111, v105
	v_sub_f32_e32 v105, v118, v250
	v_cndmask_b32_e64 v116, v116, v202, s[14:15]
	v_sub_f32_e32 v118, v177, v135
	v_cmp_gt_i32_e64 s[14:15], v219, v143
	v_fmac_f32_e32 v118, 0x3e38aa3b, v233
	s_and_b64 s[14:15], vcc, s[14:15]
	v_exp_f32_e32 v119, v105
	v_sub_f32_e32 v105, v120, v250
	v_cndmask_b32_e64 v118, v118, v202, s[14:15]
	v_sub_f32_e32 v120, v177, v136
	v_cmp_gt_i32_e64 s[14:15], v218, v143
	v_fmac_f32_e32 v120, 0x3e38aa3b, v234
	s_and_b64 s[14:15], vcc, s[14:15]
	v_exp_f32_e32 v117, v105
	v_sub_f32_e32 v105, v122, v250
	v_cndmask_b32_e64 v122, v120, v202, s[14:15]
	v_sub_f32_e32 v120, v177, v137
	v_cmp_gt_i32_e64 s[14:15], v217, v143
	v_fmac_f32_e32 v120, 0x3e38aa3b, v235
	s_and_b64 s[14:15], vcc, s[14:15]
	v_cndmask_b32_e64 v124, v120, v202, s[14:15]
	v_sub_f32_e32 v120, v177, v138
	v_cmp_gt_i32_e64 s[14:15], v216, v143
	v_fmac_f32_e32 v120, 0x3e38aa3b, v236
	s_and_b64 s[14:15], vcc, s[14:15]
	v_cndmask_b32_e64 v130, v120, v202, s[14:15]
	v_sub_f32_e32 v120, v177, v139
	v_cmp_gt_i32_e64 s[14:15], v215, v143
	v_fmac_f32_e32 v120, 0x3e38aa3b, v237
	s_and_b64 s[14:15], vcc, s[14:15]
	v_cndmask_b32_e64 v131, v120, v202, s[14:15]
	v_sub_f32_e32 v120, v177, v188
	v_cmp_gt_i32_e64 s[14:15], v214, v143
	v_fmac_f32_e32 v120, 0x3e38aa3b, v238
	s_and_b64 s[14:15], vcc, s[14:15]
	v_sub_f32_e32 v112, v177, v132
	v_cndmask_b32_e64 v132, v120, v202, s[14:15]
	v_sub_f32_e32 v120, v177, v189
	v_cmp_gt_i32_e64 s[14:15], v186, v143
	v_fmac_f32_e32 v120, 0x3e38aa3b, v239
	s_and_b64 s[14:15], vcc, s[14:15]
	v_cndmask_b32_e64 v133, v120, v202, s[14:15]
	v_sub_f32_e32 v120, v177, v190
	v_cmp_gt_i32_e64 s[14:15], v184, v143
	v_fmac_f32_e32 v120, 0x3e38aa3b, v240
	s_and_b64 s[14:15], vcc, s[14:15]
	v_cndmask_b32_e64 v136, v120, v202, s[14:15]
	v_sub_f32_e32 v120, v177, v191
	v_cmp_gt_i32_e64 s[14:15], v182, v143
	v_cndmask_b32_e32 v106, v227, v106, vcc
	v_fmac_f32_e32 v120, 0x3e38aa3b, v241
	s_and_b64 s[14:15], vcc, s[14:15]
	v_fmac_f32_e32 v112, 0x3e38aa3b, v230
	v_cndmask_b32_e64 v137, v120, v202, s[14:15]
	v_max3_f32 v120, v104, s89, v106
	v_cndmask_b32_e64 v112, v112, v202, s[12:13]
	v_max3_f32 v120, v120, v108, v110
	v_max3_f32 v120, v120, v112, v114
	v_max3_f32 v120, v120, v116, v118
	v_max3_f32 v120, v120, v122, v124
	v_max3_f32 v120, v120, v130, v131
	v_max3_f32 v120, v120, v132, v133
	v_max3_f32 v120, v120, v136, v137
	ds_bpermute_b32 v126, v204, v120
	v_exp_f32_e32 v105, v105
	v_pk_mul_f32 v[70:71], v[70:71], v[140:141] op_sel_hi:[1,0]
	v_pk_mul_f32 v[68:69], v[68:69], v[140:141] op_sel_hi:[1,0]
	v_cvt_pk_bf16_f32 v242, v127, v181
	s_waitcnt lgkmcnt(0)
	v_max_f32_e32 v126, v126, v126
	v_max_f32_e32 v120, v120, v126
	ds_bpermute_b32 v126, v203, v120
	v_cvt_pk_bf16_f32 v243, v183, v185
	v_cvt_pk_bf16_f32 v244, v187, v121
	v_cvt_pk_bf16_f32 v245, v107, v111
	v_cvt_pk_bf16_f32 v246, v119, v117
	s_waitcnt lgkmcnt(0)
; template <bool BOUND>
; DEV void attn_tile(const char* kb_, const char* vb_, const float* cl, int kt, bool diag, const int (&qrow)[2], int fr, int fq,
;                    const float (&cq2)[2], const bf16x8 (&qf)[2][2], f32x4 (&o)[2][4], float (&m2)[2], float (&l)[2]) {
;     ...
;     tmax = fmaxf(tmax, __shfl_xor(tmax, 16));
;     tmax = fmaxf(tmax, __shfl_xor(tmax, 32));
;     const float mn = fmaxf(m2[qs], tmax);
;     const float alpha = __builtin_amdgcn_exp2f(m2[qs] - mn);
;     m2[qs] = mn;
;     float ps = 0.f;
; #pragma unroll
;     for (int s = 0; s < 4; ++s)
; #pragma unroll
;       for (int j = 0; j < 4; ++j) {
;         const float pv = __builtin_amdgcn_exp2f(st[qs][s][j] - mn);
;         st[qs][s][j] = pv;
;         ps += pv;
;       }
;     l[qs] = l[qs] * alpha + ps;
; #pragma unroll
;     for (int n = 0; n < 4; ++n) { o[qs][n][0] *= alpha; o[qs][n][1] *= alpha; o[qs][n][2] *= alpha; o[qs][n][3] *= alpha; }
;     }
; #pragma unroll
;     for (int g = 0; g < 2; ++g) {
;       union { bf16x8 v; unsigned u[4]; } pk;
;       pk.u[0] = pack2bf(st[qs][2 * g][0], st[qs][2 * g][1]);
;       pk.u[1] = pack2bf(st[qs][2 * g][2], st[qs][2 * g][3]);
;       pk.u[2] = pack2bf(st[qs][2 * g + 1][0], st[qs][2 * g + 1][1]);
;       pk.u[3] = pack2bf(st[qs][2 * g + 1][2], st[qs][2 * g + 1][3]);
;       pf[qs][g] = pk.v;
;     }
; #pragma unroll
;     for (int n = 0; n < 4; ++n)
; #pragma unroll
;       for (int g = 0; g < 2; ++g) o[qs][n] = __builtin_amdgcn_mfma_f32_16x16x32_bf16(vf[n][g], pf[qs][g], o[qs][n], 0, 0, 0);
	v_max3_f32 v138, v180, v120, v126
	v_sub_f32_e32 v104, v104, v138
	v_exp_f32_e32 v126, v104
	v_sub_f32_e32 v104, v106, v138
	v_sub_f32_e32 v139, v180, v138
	v_exp_f32_e32 v180, v104
	v_sub_f32_e32 v104, v108, v138
	v_exp_f32_e32 v182, v104
	v_sub_f32_e32 v104, v110, v138
	v_exp_f32_e32 v184, v104
	v_sub_f32_e32 v104, v112, v138
	v_exp_f32_e32 v186, v104
	v_sub_f32_e32 v104, v114, v138
	v_exp_f32_e32 v120, v104
	v_sub_f32_e32 v104, v116, v138
	v_exp_f32_e32 v106, v104
	v_sub_f32_e32 v104, v118, v138
	v_pk_add_f32 v[128:129], v[126:127], 0 op_sel_hi:[1,0]
	v_exp_f32_e32 v110, v104
	v_sub_f32_e32 v104, v122, v138
	v_sub_f32_e32 v122, v136, v138
	v_exp_f32_e32 v136, v139
	v_pk_add_f32 v[128:129], v[180:181], v[128:129]
	v_exp_f32_e32 v118, v104
	v_pk_add_f32 v[128:129], v[182:183], v[128:129]
	v_sub_f32_e32 v104, v124, v138
	v_sub_f32_e32 v112, v132, v138
	v_pk_add_f32 v[128:129], v[184:185], v[128:129]
	v_exp_f32_e32 v116, v104
	v_sub_f32_e32 v104, v130, v138
	v_sub_f32_e32 v108, v131, v138
	v_exp_f32_e32 v114, v112
	v_sub_f32_e32 v112, v133, v138
	v_sub_f32_e32 v124, v137, v138
	v_mov_b32_e32 v137, v140
	v_pk_add_f32 v[134:135], v[186:187], v[128:129]
	v_exp_f32_e32 v104, v104
	v_exp_f32_e32 v108, v108
	v_exp_f32_e32 v112, v112
	v_exp_f32_e32 v122, v122
	v_exp_f32_e32 v124, v124
	v_pk_mul_f32 v[66:67], v[66:67], v[136:137] op_sel_hi:[1,0]
	v_pk_mul_f32 v[64:65], v[64:65], v[136:137] op_sel_hi:[1,0]
	v_cvt_pk_bf16_f32 v126, v126, v180
	v_cvt_pk_bf16_f32 v127, v182, v184
	v_cvt_pk_bf16_f32 v128, v186, v120
	v_cvt_pk_bf16_f32 v129, v106, v110
	v_mfma_f32_16x16x32_bf16 v[68:71], v[92:95], v[242:245], v[68:71]
	v_cvt_pk_bf16_f32 v247, v105, v109
	v_cvt_pk_bf16_f32 v248, v115, v113
	v_cvt_pk_bf16_f32 v249, v123, v125
	v_mfma_f32_16x16x32_bf16 v[64:67], v[92:95], v[126:129], v[64:67]
	v_mul_f32_e64 v42, v42, v140
	v_mul_f32_e64 v43, v43, v140
	v_pk_mul_f32 v[40:41], v[40:41], v[140:141] op_sel_hi:[1,0]
	v_cvt_pk_bf16_f32 v130, v118, v116
	v_cvt_pk_bf16_f32 v131, v104, v108
	v_cvt_pk_bf16_f32 v132, v114, v112
	v_cvt_pk_bf16_f32 v133, v122, v124
	v_pk_mul_f32 v[10:11], v[10:11], v[136:137] op_sel_hi:[1,0]
	v_pk_mul_f32 v[8:9], v[8:9], v[136:137] op_sel_hi:[1,0]
	v_mfma_f32_16x16x32_bf16 v[68:71], v[88:91], v[246:249], v[68:71]
	v_mul_f32_e64 v62, v62, v140
	v_mul_f32_e64 v63, v63, v140
	v_pk_mul_f32 v[60:61], v[60:61], v[140:141] op_sel_hi:[1,0]
	v_pk_mul_f32 v[6:7], v[6:7], v[136:137] op_sel_hi:[1,0]
	v_mfma_f32_16x16x32_bf16 v[40:43], v[84:87], v[242:245], v[40:43]
	v_mul_f32_e64 v4, v4, v136
	v_mul_f32_e64 v5, v5, v136
	v_pk_mul_f32 v[22:23], v[22:23], v[140:141] op_sel_hi:[1,0]
	v_pk_mul_f32 v[20:21], v[20:21], v[140:141] op_sel_hi:[1,0]
	v_mfma_f32_16x16x32_bf16 v[64:67], v[88:91], v[130:133], v[64:67]
	v_add_f32_e64 v88, v120, v134
	v_add_f32_e64 v89, v121, v135
	v_pk_mul_f32 v[2:3], v[2:3], v[136:137] op_sel_hi:[1,0]
	v_pk_mul_f32 v[0:1], v[0:1], v[136:137] op_sel_hi:[1,0]
	v_mfma_f32_16x16x32_bf16 v[8:11], v[84:87], v[126:129], v[8:11]
	v_add_f32_e64 v84, v106, v88
	v_add_f32_e64 v85, v107, v89
	v_mov_b32_e32 v181, v250
	v_pk_add_f32 v[84:85], v[110:111], v[84:85]
	v_mfma_f32_16x16x32_bf16 v[40:43], v[80:83], v[246:249], v[40:43]
	v_add_f32_e64 v84, v118, v84
	v_add_f32_e64 v85, v119, v85
	v_mov_b32_e32 v180, v138
	v_mfma_f32_16x16x32_bf16 v[60:63], v[76:79], v[242:245], v[60:63]
	v_mfma_f32_16x16x32_bf16 v[8:11], v[80:83], v[130:133], v[8:11]
	v_add_f32_e64 v80, v116, v84
	v_add_f32_e64 v81, v117, v85
	v_mfma_f32_16x16x32_bf16 v[4:7], v[76:79], v[126:129], v[4:7]
	v_add_f32_e64 v76, v104, v80
	v_add_f32_e64 v77, v105, v81
	v_pk_add_f32 v[76:77], v[108:109], v[76:77]
	v_mfma_f32_16x16x32_bf16 v[20:23], v[100:103], v[242:245], v[20:23]
	v_add_f32_e64 v76, v114, v76
	v_add_f32_e64 v77, v115, v77
	v_mfma_f32_16x16x32_bf16 v[0:3], v[100:103], v[126:129], v[0:3]
	v_mfma_f32_16x16x32_bf16 v[60:63], v[72:75], v[246:249], v[60:63]
	v_mfma_f32_16x16x32_bf16 v[4:7], v[72:75], v[130:133], v[4:7]
	v_add_f32_e64 v72, v112, v76
	v_add_f32_e64 v73, v113, v77
	v_pk_add_f32 v[72:73], v[122:123], v[72:73]
	v_mfma_f32_16x16x32_bf16 v[20:23], v[96:99], v[246:249], v[20:23]
	v_add_f32_e64 v72, v124, v72
	v_add_f32_e64 v73, v125, v73
	v_pk_fma_f32 v[178:179], v[178:179], v[136:137], v[72:73]
	v_mfma_f32_16x16x32_bf16 v[0:3], v[96:99], v[130:133], v[0:3]

; template <bool BOUND>
; DEV void attn_tile(const char* kb_, const char* vb_, const float* cl, int kt, bool diag, const int (&qrow)[2], int fr, int fq,
;                    const float (&cq2)[2], const bf16x8 (&qf)[2][2], f32x4 (&o)[2][4], float (&m2)[2], float (&l)[2]) {
;     ...
; #pragma unroll
;   for (int s = 0; s < 4; ++s) {
;     const bf16x8 a0 = *(const bf16x8*)(kb_ + (s * 16 + fr) * 144 + fq * 16);
;     const bf16x8 a1 = *(const bf16x8*)(kb_ + (s * 16 + fr) * 144 + 64 + fq * 16);
; #pragma unroll
;     for (int qs = 0; qs < 2; ++qs) {
;       f32x4 z = f32x4{0.f, 0.f, 0.f, 0.f};
;       z = __builtin_amdgcn_mfma_f32_16x16x32_bf16(a0, qf[qs][0], z, 0, 0, 0);
;       st[qs][s] = __builtin_amdgcn_mfma_f32_16x16x32_bf16(a1, qf[qs][1], z, 0, 0, 0);
;     }
;   }
;   bf16x8 vf[4][2];
; #pragma unroll
;   for (int n = 0; n < 4; ++n)
; #pragma unroll
;     for (int g = 0; g < 2; ++g) {
;       const char* va = vb_ + (n * 16 + fr) * 144 + (g * 32 + fq * 4) * 2;
;       union { bf16x8 v; uint2 u[2]; } av;
;       av.u[0] = *(const uint2*)va;
;       av.u[1] = *(const uint2*)(va + 32);
;       vf[n][g] = av.v;
;     }
;   bf16x8 pf[2][2];
; #pragma unroll
;   for (int qs = 0; qs < 2; ++qs) {
;     if constexpr (BOUND) {
;       float ps = 0.f;
; #pragma unroll
;       for (int s = 0; s < 4; ++s) {
;         const float4 ck = *(const float4*)(cl + kt * 64 + s * 16 + fq * 4);
;         const float ckk[4] = {ck.x, ck.y, ck.z, ck.w};
; #pragma unroll
;         for (int j = 0; j < 4; ++j) {
;           float x = st[qs][s][j] * SC2 + (cq2[qs] - ckk[j]);
;           if (diag) {
;             const int key = kt * 64 + s * 16 + fq * 4 + j;
;             if (key > qrow[qs]) x = -1e30f;
;           }
;           const float pv = __builtin_amdgcn_exp2f(x);
;           st[qs][s][j] = pv;
;           ps += pv;
;         }
;       }
;       l[qs] += ps;
;     ...
; #pragma unroll
;     for (int g = 0; g < 2; ++g) {
;       union { bf16x8 v; unsigned u[4]; } pk;
;       pk.u[0] = pack2bf(st[qs][2 * g][0], st[qs][2 * g][1]);
;       pk.u[1] = pack2bf(st[qs][2 * g][2], st[qs][2 * g][3]);
;       pk.u[2] = pack2bf(st[qs][2 * g + 1][0], st[qs][2 * g + 1][1]);
;       pk.u[3] = pack2bf(st[qs][2 * g + 1][2], st[qs][2 * g + 1][3]);
;       pf[qs][g] = pk.v;
;     }
; #pragma unroll
;     for (int n = 0; n < 4; ++n)
; #pragma unroll
.Lattn_nm0:
	v_mfma_f32_16x16x32_bf16 v[230:233], v[132:135], v[12:15], 0
	ds_read_b128 v[242:245], v140 offset:36992
	v_mfma_f32_16x16x32_bf16 v[230:233], v[128:131], v[16:19], v[230:233]
	v_mfma_f32_16x16x32_bf16 v[234:237], v[132:135], v[28:31], 0
	v_mfma_f32_16x16x32_bf16 v[238:241], v[124:127], v[12:15], 0
	s_nop 5
	v_fmac_f32_e32 v139, 0x3e38aa3b, v231
	v_fmac_f32_e32 v137, 0x3e38aa3b, v230
	v_fmac_f32_e32 v138, 0x3e38aa3b, v232
	v_fmac_f32_e32 v136, 0x3e38aa3b, v233
	ds_read_b128 v[230:233], v140 offset:36928
	v_mfma_f32_16x16x32_bf16 v[234:237], v[128:131], v[24:27], v[234:237]
	v_mfma_f32_16x16x32_bf16 v[238:241], v[120:123], v[16:19], v[238:241]
	v_exp_f32_e32 v129, v138
	v_exp_f32_e32 v131, v136
	v_mfma_f32_16x16x32_bf16 v[124:127], v[124:127], v[28:31], 0
	s_waitcnt lgkmcnt(0)
	v_sub_f32_e32 v128, v157, v230
	s_nop 0
	s_nop 1
	v_fmac_f32_e32 v128, 0x3e38aa3b, v238
	v_mfma_f32_16x16x32_bf16 v[124:127], v[120:123], v[24:27], v[124:127]
	v_exp_f32_e32 v121, v128
	v_sub_f32_e32 v120, v157, v231
	v_mfma_f32_16x16x32_bf16 v[246:249], v[116:119], v[12:15], 0
	v_fmac_f32_e32 v120, 0x3e38aa3b, v239
	v_mfma_f32_16x16x32_bf16 v[116:119], v[116:119], v[28:31], 0
	v_exp_f32_e32 v123, v120
	v_sub_f32_e32 v120, v157, v232
	v_fmac_f32_e32 v120, 0x3e38aa3b, v240
	v_mfma_f32_16x16x32_bf16 v[246:249], v[112:115], v[16:19], v[246:249]
	v_exp_f32_e32 v133, v139
	v_mfma_f32_16x16x32_bf16 v[116:119], v[112:115], v[24:27], v[116:119]
	v_exp_f32_e32 v113, v120
	v_sub_f32_e32 v112, v157, v233
	v_mfma_f32_16x16x32_bf16 v[250:253], v[108:111], v[12:15], 0
	v_fmac_f32_e32 v112, 0x3e38aa3b, v241
	v_mfma_f32_16x16x32_bf16 v[108:111], v[108:111], v[28:31], 0
	v_exp_f32_e32 v115, v112
	v_sub_f32_e32 v112, v157, v242
	v_fmac_f32_e32 v112, 0x3e38aa3b, v246
	s_nop 0
	v_mfma_f32_16x16x32_bf16 v[238:241], v[104:107], v[16:19], v[250:253]
	v_sub_f32_e32 v114, v177, v231
	v_fmac_f32_e32 v114, 0x3e38aa3b, v125
	v_sub_f32_e32 v120, v177, v232
	v_mfma_f32_16x16x32_bf16 v[250:253], v[104:107], v[24:27], v[108:111]
	v_exp_f32_e32 v105, v112
	v_sub_f32_e32 v104, v157, v243
	v_fmac_f32_e32 v104, 0x3e38aa3b, v247
	v_exp_f32_e32 v107, v104
	v_sub_f32_e32 v104, v157, v244
	v_fmac_f32_e32 v104, 0x3e38aa3b, v248
	v_exp_f32_e32 v109, v104
	v_sub_f32_e32 v104, v157, v245
	v_fmac_f32_e32 v104, 0x3e38aa3b, v249
	ds_read_b128 v[246:249], v140 offset:37056
	v_sub_f32_e32 v112, v177, v230
	v_fmac_f32_e32 v112, 0x3e38aa3b, v124
	v_exp_f32_e32 v111, v104
	s_waitcnt lgkmcnt(0)
	v_sub_f32_e32 v104, v157, v246
	v_fmac_f32_e32 v104, 0x3e38aa3b, v238
	v_exp_f32_e32 v135, v104
	v_sub_f32_e32 v104, v157, v247
	v_fmac_f32_e32 v120, 0x3e38aa3b, v126
	v_fmac_f32_e32 v104, 0x3e38aa3b, v239
	v_mov_b32_e32 v124, v120
	v_sub_f32_e32 v120, v177, v233
	v_fmac_f32_e32 v120, 0x3e38aa3b, v127
	v_exp_f32_e32 v139, v104
	v_sub_f32_e32 v104, v157, v248
	v_mov_b32_e32 v125, v120
	v_sub_f32_e32 v120, v177, v242
	v_fmac_f32_e32 v104, 0x3e38aa3b, v240
	v_fmac_f32_e32 v120, 0x3e38aa3b, v116
	v_mov_b32_e32 v116, v120
	v_sub_f32_e32 v120, v177, v243
	v_exp_f32_e32 v183, v104
	v_sub_f32_e32 v104, v157, v249
	v_fmac_f32_e32 v120, 0x3e38aa3b, v117
	v_fmac_f32_e32 v104, 0x3e38aa3b, v241
	v_mov_b32_e32 v117, v120
	v_sub_f32_e32 v120, v177, v244
	v_fmac_f32_e32 v120, 0x3e38aa3b, v118
	v_fmac_f32_e32 v228, 0x3e38aa3b, v234
	v_mov_b32_e32 v118, v120
	v_sub_f32_e32 v120, v177, v245
	v_exp_f32_e32 v185, v104
	v_fmac_f32_e32 v227, 0x3e38aa3b, v235
	v_fmac_f32_e32 v120, 0x3e38aa3b, v119
	v_mov_b32_e32 v119, v120
	v_sub_f32_e32 v120, v177, v246
	v_fmac_f32_e32 v226, 0x3e38aa3b, v236
	v_fmac_f32_e32 v120, 0x3e38aa3b, v250
	v_sub_f32_e32 v122, v177, v247
	v_fmac_f32_e32 v225, 0x3e38aa3b, v237
	v_fmac_f32_e32 v122, 0x3e38aa3b, v251
	v_sub_f32_e32 v126, v177, v248
	v_exp_f32_e32 v137, v137
	v_fmac_f32_e32 v126, 0x3e38aa3b, v252
	v_exp_f32_e32 v134, v120
	v_exp_f32_e32 v138, v122
	v_exp_f32_e32 v136, v228
	v_exp_f32_e32 v132, v227
	v_exp_f32_e32 v128, v226
	v_exp_f32_e32 v130, v225
	v_exp_f32_e32 v120, v112
	v_exp_f32_e32 v122, v114
	v_exp_f32_e32 v112, v124
	v_exp_f32_e32 v114, v125
	v_sub_f32_e32 v127, v177, v249
	v_fmac_f32_e32 v127, 0x3e38aa3b, v253
	v_cvt_pk_bf16_f32 v238, v137, v133
	v_cvt_pk_bf16_f32 v239, v129, v131
	v_cvt_pk_bf16_f32 v240, v121, v123
	v_cvt_pk_bf16_f32 v241, v113, v115
	v_exp_f32_e32 v182, v126
	v_exp_f32_e32 v104, v116
	v_exp_f32_e32 v106, v117
	v_exp_f32_e32 v108, v118
	v_exp_f32_e32 v110, v119
	v_exp_f32_e32 v184, v127
	v_cvt_pk_bf16_f32 v116, v136, v132
	v_cvt_pk_bf16_f32 v117, v128, v130
	v_cvt_pk_bf16_f32 v118, v120, v122
	v_cvt_pk_bf16_f32 v119, v112, v114
	v_mfma_f32_16x16x32_bf16 v[68:71], v[92:95], v[238:241], v[68:71]
	v_cvt_pk_bf16_f32 v188, v105, v107
	v_cvt_pk_bf16_f32 v189, v109, v111
	v_cvt_pk_bf16_f32 v190, v135, v139
	v_mfma_f32_16x16x32_bf16 v[64:67], v[92:95], v[116:119], v[64:67]
	v_cvt_pk_bf16_f32 v191, v183, v185
	v_cvt_pk_bf16_f32 v124, v104, v106
	v_cvt_pk_bf16_f32 v125, v108, v110
	v_cvt_pk_bf16_f32 v126, v134, v138
	v_cvt_pk_bf16_f32 v127, v182, v184
	v_mfma_f32_16x16x32_bf16 v[68:71], v[88:91], v[188:191], v[68:71]
	s_nop 0
	v_mfma_f32_16x16x32_bf16 v[64:67], v[88:91], v[124:127], v[64:67]
	v_add_f32_e64 v88, v136, 0
	v_add_f32_e64 v89, v137, 0
	v_pk_add_f32 v[88:89], v[88:89], v[132:133]
	v_mfma_f32_16x16x32_bf16 v[40:43], v[84:87], v[238:241], v[40:43]
	v_mfma_f32_16x16x32_bf16 v[8:11], v[84:87], v[116:119], v[8:11]
	v_add_f32_e64 v84, v128, v88
	v_add_f32_e64 v85, v129, v89
	v_pk_add_f32 v[84:85], v[130:131], v[84:85]
	v_mfma_f32_16x16x32_bf16 v[40:43], v[80:83], v[188:191], v[40:43]
	v_add_f32_e64 v84, v84, v120
	v_add_f32_e64 v85, v85, v121
	v_mfma_f32_16x16x32_bf16 v[8:11], v[80:83], v[124:127], v[8:11]
	v_add_f32_e64 v80, v122, v84
	v_add_f32_e64 v81, v123, v85
	v_pk_add_f32 v[80:81], v[112:113], v[80:81]
	v_mfma_f32_16x16x32_bf16 v[60:63], v[76:79], v[238:241], v[60:63]
	v_add_f32_e64 v80, v114, v80
	v_add_f32_e64 v81, v115, v81
	v_mfma_f32_16x16x32_bf16 v[4:7], v[76:79], v[116:119], v[4:7]
	v_add_f32_e64 v76, v104, v80
	v_add_f32_e64 v77, v105, v81
	v_pk_add_f32 v[76:77], v[106:107], v[76:77]
	v_mfma_f32_16x16x32_bf16 v[20:23], v[100:103], v[238:241], v[20:23]
	v_add_f32_e64 v76, v108, v76
	v_add_f32_e64 v77, v109, v77
	v_mfma_f32_16x16x32_bf16 v[0:3], v[100:103], v[116:119], v[0:3]
	v_mfma_f32_16x16x32_bf16 v[60:63], v[72:75], v[188:191], v[60:63]
	v_mfma_f32_16x16x32_bf16 v[4:7], v[72:75], v[124:127], v[4:7]
	v_add_f32_e64 v72, v110, v76
	v_add_f32_e64 v73, v111, v77
	v_pk_add_f32 v[72:73], v[134:135], v[72:73]
	v_mfma_f32_16x16x32_bf16 v[20:23], v[96:99], v[188:191], v[20:23]
	v_add_f32_e64 v72, v138, v72
	v_add_f32_e64 v73, v139, v73
	v_pk_add_f32 v[72:73], v[182:183], v[72:73]
	v_mfma_f32_16x16x32_bf16 v[0:3], v[96:99], v[124:127], v[0:3]
	v_add_f32_e64 v72, v184, v72
	v_add_f32_e64 v73, v185, v73
	v_pk_add_f32 v[178:179], v[178:179], v[72:73]
	s_branch .LBB0_824
; template <bool BOUND>
; DEV void attn_tile(const char* kb_, const char* vb_, const float* cl, int kt, bool diag, const int (&qrow)[2], int fr, int fq,
;                    const float (&cq2)[2], const bf16x8 (&qf)[2][2], f32x4 (&o)[2][4], float (&m2)[2], float (&l)[2]) {
;     ...
; #pragma unroll
;   for (int s = 0; s < 4; ++s) {
;     const bf16x8 a0 = *(const bf16x8*)(kb_ + (s * 16 + fr) * 144 + fq * 16);
;     const bf16x8 a1 = *(const bf16x8*)(kb_ + (s * 16 + fr) * 144 + 64 + fq * 16);
; #pragma unroll
;     for (int qs = 0; qs < 2; ++qs) {
;       f32x4 z = f32x4{0.f, 0.f, 0.f, 0.f};
;       z = __builtin_amdgcn_mfma_f32_16x16x32_bf16(a0, qf[qs][0], z, 0, 0, 0);
;       st[qs][s] = __builtin_amdgcn_mfma_f32_16x16x32_bf16(a1, qf[qs][1], z, 0, 0, 0);
;     }
;   }
;   bf16x8 vf[4][2];
; #pragma unroll
;   for (int n = 0; n < 4; ++n)
; #pragma unroll
;     for (int g = 0; g < 2; ++g) {
;       const char* va = vb_ + (n * 16 + fr) * 144 + (g * 32 + fq * 4) * 2;
;       union { bf16x8 v; uint2 u[2]; } av;
;       av.u[0] = *(const uint2*)va;
;       av.u[1] = *(const uint2*)(va + 32);
;       vf[n][g] = av.v;
;     }
;   bf16x8 pf[2][2];
; #pragma unroll
;   for (int qs = 0; qs < 2; ++qs) {
;     if constexpr (BOUND) {
;       float ps = 0.f;
; #pragma unroll
;       for (int s = 0; s < 4; ++s) {
;         const float4 ck = *(const float4*)(cl + kt * 64 + s * 16 + fq * 4);
;         const float ckk[4] = {ck.x, ck.y, ck.z, ck.w};
; #pragma unroll
;         for (int j = 0; j < 4; ++j) {
;           float x = st[qs][s][j] * SC2 + (cq2[qs] - ckk[j]);
;           if (diag) {
;             const int key = kt * 64 + s * 16 + fq * 4 + j;
;             if (key > qrow[qs]) x = -1e30f;
;           }
;           const float pv = __builtin_amdgcn_exp2f(x);
;           st[qs][s][j] = pv;
;           ps += pv;
;         }
;       }
;       l[qs] += ps;
;     ...
; #pragma unroll
;     for (int g = 0; g < 2; ++g) {
;       union { bf16x8 v; unsigned u[4]; } pk;
;       pk.u[0] = pack2bf(st[qs][2 * g][0], st[qs][2 * g][1]);
;       pk.u[1] = pack2bf(st[qs][2 * g][2], st[qs][2 * g][3]);
;       pk.u[2] = pack2bf(st[qs][2 * g + 1][0], st[qs][2 * g + 1][1]);
;       pk.u[3] = pack2bf(st[qs][2 * g + 1][2], st[qs][2 * g + 1][3]);
;       pf[qs][g] = pk.v;
;     }
; #pragma unroll
;     for (int n = 0; n < 4; ++n)
; #pragma unroll
.Lattn_nm1:
	v_mfma_f32_16x16x32_bf16 v[188:191], v[132:135], v[12:15], 0
	ds_read_b128 v[238:241], v140 offset:36992
	v_mfma_f32_16x16x32_bf16 v[188:191], v[128:131], v[16:19], v[188:191]
	v_mfma_f32_16x16x32_bf16 v[230:233], v[132:135], v[28:31], 0
	v_mfma_f32_16x16x32_bf16 v[234:237], v[124:127], v[12:15], 0
	s_nop 5
	v_fmac_f32_e32 v139, 0x3e38aa3b, v189
	v_fmac_f32_e32 v137, 0x3e38aa3b, v188
	v_fmac_f32_e32 v138, 0x3e38aa3b, v190
	v_fmac_f32_e32 v136, 0x3e38aa3b, v191
	ds_read_b128 v[188:191], v140 offset:36928
	v_mfma_f32_16x16x32_bf16 v[230:233], v[128:131], v[24:27], v[230:233]
	v_mfma_f32_16x16x32_bf16 v[234:237], v[120:123], v[16:19], v[234:237]
	v_exp_f32_e32 v129, v138
	v_exp_f32_e32 v131, v136
	v_mfma_f32_16x16x32_bf16 v[124:127], v[124:127], v[28:31], 0
	s_waitcnt lgkmcnt(0)
	v_sub_f32_e32 v128, v157, v188
	s_nop 0
	s_nop 1
	v_fmac_f32_e32 v128, 0x3e38aa3b, v234
	v_mfma_f32_16x16x32_bf16 v[124:127], v[120:123], v[24:27], v[124:127]
	v_exp_f32_e32 v121, v128
	v_sub_f32_e32 v120, v157, v189
	v_mfma_f32_16x16x32_bf16 v[242:245], v[116:119], v[12:15], 0
	v_fmac_f32_e32 v120, 0x3e38aa3b, v235
	v_mfma_f32_16x16x32_bf16 v[116:119], v[116:119], v[28:31], 0
	v_exp_f32_e32 v123, v120
	v_sub_f32_e32 v120, v157, v190
	v_fmac_f32_e32 v120, 0x3e38aa3b, v236
	v_mfma_f32_16x16x32_bf16 v[242:245], v[112:115], v[16:19], v[242:245]
	v_exp_f32_e32 v133, v139
	v_mfma_f32_16x16x32_bf16 v[116:119], v[112:115], v[24:27], v[116:119]
	v_exp_f32_e32 v113, v120
	v_sub_f32_e32 v112, v157, v191
	v_mfma_f32_16x16x32_bf16 v[246:249], v[108:111], v[12:15], 0
	v_fmac_f32_e32 v112, 0x3e38aa3b, v237
	v_mfma_f32_16x16x32_bf16 v[108:111], v[108:111], v[28:31], 0
	v_exp_f32_e32 v115, v112
	v_sub_f32_e32 v112, v157, v238
	v_fmac_f32_e32 v112, 0x3e38aa3b, v242
	s_nop 0
	v_mfma_f32_16x16x32_bf16 v[234:237], v[104:107], v[16:19], v[246:249]
	v_sub_f32_e32 v114, v177, v189
	v_fmac_f32_e32 v114, 0x3e38aa3b, v125
	v_sub_f32_e32 v120, v177, v190
	v_mfma_f32_16x16x32_bf16 v[246:249], v[104:107], v[24:27], v[108:111]
	v_exp_f32_e32 v105, v112
	v_sub_f32_e32 v104, v157, v239
	v_fmac_f32_e32 v104, 0x3e38aa3b, v243
	v_exp_f32_e32 v107, v104
	v_sub_f32_e32 v104, v157, v240
	v_fmac_f32_e32 v104, 0x3e38aa3b, v244
	v_exp_f32_e32 v109, v104
	v_sub_f32_e32 v104, v157, v241
	v_fmac_f32_e32 v104, 0x3e38aa3b, v245
	ds_read_b128 v[242:245], v140 offset:37056
	v_sub_f32_e32 v112, v177, v188
	v_fmac_f32_e32 v112, 0x3e38aa3b, v124
	v_exp_f32_e32 v111, v104
	s_waitcnt lgkmcnt(0)
	v_sub_f32_e32 v104, v157, v242
	v_fmac_f32_e32 v104, 0x3e38aa3b, v234
	v_exp_f32_e32 v135, v104
	v_sub_f32_e32 v104, v157, v243
	v_fmac_f32_e32 v120, 0x3e38aa3b, v126
	v_fmac_f32_e32 v104, 0x3e38aa3b, v235
	v_mov_b32_e32 v124, v120
	v_sub_f32_e32 v120, v177, v191
	v_fmac_f32_e32 v120, 0x3e38aa3b, v127
	v_exp_f32_e32 v139, v104
	v_sub_f32_e32 v104, v157, v244
	v_mov_b32_e32 v125, v120
	v_sub_f32_e32 v120, v177, v238
	v_fmac_f32_e32 v104, 0x3e38aa3b, v236
	v_fmac_f32_e32 v120, 0x3e38aa3b, v116
	v_mov_b32_e32 v116, v120
	v_sub_f32_e32 v120, v177, v239
	v_exp_f32_e32 v183, v104
	v_sub_f32_e32 v104, v157, v245
	v_fmac_f32_e32 v120, 0x3e38aa3b, v117
	v_fmac_f32_e32 v104, 0x3e38aa3b, v237
	v_mov_b32_e32 v117, v120
	v_sub_f32_e32 v120, v177, v240
	v_fmac_f32_e32 v120, 0x3e38aa3b, v118
	v_fmac_f32_e32 v228, 0x3e38aa3b, v230
	v_mov_b32_e32 v118, v120
	v_sub_f32_e32 v120, v177, v241
	v_exp_f32_e32 v185, v104
	v_fmac_f32_e32 v227, 0x3e38aa3b, v231
	v_fmac_f32_e32 v120, 0x3e38aa3b, v119
	v_mov_b32_e32 v119, v120
	v_sub_f32_e32 v120, v177, v242
	v_fmac_f32_e32 v226, 0x3e38aa3b, v232
	v_fmac_f32_e32 v120, 0x3e38aa3b, v246
	v_sub_f32_e32 v122, v177, v243
	v_fmac_f32_e32 v225, 0x3e38aa3b, v233
	v_fmac_f32_e32 v122, 0x3e38aa3b, v247
	v_sub_f32_e32 v126, v177, v244
	v_exp_f32_e32 v137, v137
	v_fmac_f32_e32 v126, 0x3e38aa3b, v248
	v_exp_f32_e32 v134, v120
	v_exp_f32_e32 v138, v122
	v_exp_f32_e32 v136, v228
	v_exp_f32_e32 v132, v227
	v_exp_f32_e32 v128, v226
	v_exp_f32_e32 v130, v225
	v_exp_f32_e32 v120, v112
	v_exp_f32_e32 v122, v114
	v_exp_f32_e32 v112, v124
	v_exp_f32_e32 v114, v125
	v_sub_f32_e32 v127, v177, v245
	v_fmac_f32_e32 v127, 0x3e38aa3b, v249
	v_cvt_pk_bf16_f32 v234, v137, v133
	v_cvt_pk_bf16_f32 v235, v129, v131
	v_cvt_pk_bf16_f32 v236, v121, v123
	v_cvt_pk_bf16_f32 v237, v113, v115
	v_exp_f32_e32 v182, v126
	v_exp_f32_e32 v104, v116
	v_exp_f32_e32 v106, v117
	v_exp_f32_e32 v108, v118
	v_exp_f32_e32 v110, v119
	v_exp_f32_e32 v184, v127
	v_cvt_pk_bf16_f32 v116, v136, v132
	v_cvt_pk_bf16_f32 v117, v128, v130
	v_cvt_pk_bf16_f32 v118, v120, v122
	v_cvt_pk_bf16_f32 v119, v112, v114
	v_mfma_f32_16x16x32_bf16 v[68:71], v[92:95], v[234:237], v[68:71]
	v_cvt_pk_bf16_f32 v250, v105, v107
	v_cvt_pk_bf16_f32 v251, v109, v111
	v_cvt_pk_bf16_f32 v252, v135, v139
	v_mfma_f32_16x16x32_bf16 v[64:67], v[92:95], v[116:119], v[64:67]
	v_cvt_pk_bf16_f32 v253, v183, v185
	v_cvt_pk_bf16_f32 v124, v104, v106
	v_cvt_pk_bf16_f32 v125, v108, v110
	v_cvt_pk_bf16_f32 v126, v134, v138
	v_cvt_pk_bf16_f32 v127, v182, v184
	v_mfma_f32_16x16x32_bf16 v[68:71], v[88:91], v[250:253], v[68:71]
	s_nop 0
	v_mfma_f32_16x16x32_bf16 v[64:67], v[88:91], v[124:127], v[64:67]
	v_add_f32_e64 v88, v136, 0
	v_add_f32_e64 v89, v137, 0
	v_pk_add_f32 v[88:89], v[88:89], v[132:133]
	v_mfma_f32_16x16x32_bf16 v[40:43], v[84:87], v[234:237], v[40:43]
	v_mfma_f32_16x16x32_bf16 v[8:11], v[84:87], v[116:119], v[8:11]
	v_add_f32_e64 v84, v128, v88
	v_add_f32_e64 v85, v129, v89
	v_pk_add_f32 v[84:85], v[130:131], v[84:85]
	v_mfma_f32_16x16x32_bf16 v[40:43], v[80:83], v[250:253], v[40:43]
	v_add_f32_e64 v84, v84, v120
	v_add_f32_e64 v85, v85, v121
	v_mfma_f32_16x16x32_bf16 v[8:11], v[80:83], v[124:127], v[8:11]
	v_add_f32_e64 v80, v122, v84
	v_add_f32_e64 v81, v123, v85
	v_pk_add_f32 v[80:81], v[112:113], v[80:81]
	v_mfma_f32_16x16x32_bf16 v[60:63], v[76:79], v[234:237], v[60:63]
	v_add_f32_e64 v80, v114, v80
	v_add_f32_e64 v81, v115, v81
	v_mfma_f32_16x16x32_bf16 v[4:7], v[76:79], v[116:119], v[4:7]
	v_add_f32_e64 v76, v104, v80
	v_add_f32_e64 v77, v105, v81
	v_pk_add_f32 v[76:77], v[106:107], v[76:77]
	v_mfma_f32_16x16x32_bf16 v[20:23], v[100:103], v[234:237], v[20:23]
	v_add_f32_e64 v76, v108, v76
	v_add_f32_e64 v77, v109, v77
	v_mfma_f32_16x16x32_bf16 v[0:3], v[100:103], v[116:119], v[0:3]
	v_mfma_f32_16x16x32_bf16 v[60:63], v[72:75], v[250:253], v[60:63]
	v_mfma_f32_16x16x32_bf16 v[4:7], v[72:75], v[124:127], v[4:7]
	v_add_f32_e64 v72, v110, v76
	v_add_f32_e64 v73, v111, v77
	v_pk_add_f32 v[72:73], v[134:135], v[72:73]
	v_mfma_f32_16x16x32_bf16 v[20:23], v[96:99], v[250:253], v[20:23]
	v_add_f32_e64 v72, v138, v72
	v_add_f32_e64 v73, v139, v73
	v_pk_add_f32 v[72:73], v[182:183], v[72:73]
	v_mfma_f32_16x16x32_bf16 v[0:3], v[96:99], v[124:127], v[0:3]
	v_add_f32_e64 v72, v184, v72
	v_add_f32_e64 v73, v185, v73
	v_pk_add_f32 v[178:179], v[178:179], v[72:73]
	s_branch .LBB0_846
